# GEMM K-loop variant: DMA issue threaded through the first MFMA group only
# speedup vs baseline: 1.0157x; 1.0157x over previous
.LBB0_212:
	s_add_i32 s1, s0, 0x10000
	s_and_b32 s11, s1, 0x10000
	s_waitcnt vmcnt(0)
	s_barrier
	s_and_b32 s0, s0, 0x10000
	s_add_i32 s0, s0, 0
	v_add_u32_e32 v155, s0, v153
	v_add_u32_e32 v164, v155, v151
	ds_read_b128 v[156:159], v164
	ds_read_b128 v[160:163], v164 offset:2048
	ds_read_b128 v[178:181], v164 offset:4096
	ds_read_b128 v[182:185], v164 offset:6144
	v_add_u32_e32 v249, v155, v150
	v_add_u32_e32 v164, s0, v154
	v_add_u32_e32 v165, v164, v151
	ds_read_b128 v[186:189], v165 offset:32768
	ds_read_b128 v[192:195], v165 offset:34816
	ds_read_b128 v[198:201], v165 offset:36864
	ds_read_b128 v[204:207], v165 offset:38912
	v_add_u32_e32 v248, v164, v150
	v_add_u32_e32 v251, s11, v152
	v_add_u32_e32 v240, 0x2000, v251
	v_readfirstlane_b32 s11, v251
	v_lshl_add_u64 v[174:175], v[144:145], 0, s[8:9]
	s_mov_b32 m0, s11
	v_readfirstlane_b32 s11, v240
	v_add_u32_e32 v240, 0x4000, v251
	global_load_lds_dwordx4 v[174:175], off
	v_lshl_add_u64 v[174:175], v[134:135], 0, s[8:9]
	s_mov_b32 m0, s11
	s_waitcnt lgkmcnt(0)
	v_mfma_f32_16x16x32_bf16 v[124:127], v[156:159], v[186:189], v[124:127]
	ds_read_b128 v[224:227], v165 offset:40960
	v_mfma_f32_16x16x32_bf16 v[120:123], v[156:159], v[192:195], v[120:123]
	ds_read_b128 v[228:231], v165 offset:43008
	v_readfirstlane_b32 s11, v240
	v_add_u32_e32 v240, 0x6000, v251
	global_load_lds_dwordx4 v[174:175], off
	v_mfma_f32_16x16x32_bf16 v[116:119], v[156:159], v[198:201], v[116:119]
	ds_read_b128 v[232:235], v165 offset:45056
	v_lshl_add_u64 v[174:175], v[132:133], 0, s[8:9]
	s_mov_b32 m0, s11
	v_readfirstlane_b32 s11, v240
	v_mfma_f32_16x16x32_bf16 v[112:115], v[156:159], v[204:207], v[112:115]
	ds_read_b128 v[236:239], v165 offset:47104
	global_load_lds_dwordx4 v[174:175], off
	v_lshl_add_u64 v[174:175], v[130:131], 0, s[8:9]
	s_mov_b32 m0, s11
	v_mfma_f32_16x16x32_bf16 v[104:107], v[160:163], v[186:189], v[104:107]
	ds_read_b128 v[208:211], v249
	v_add_u32_e32 v250, 0x8000, v251
	global_load_lds_dwordx4 v[174:175], off
	v_lshl_add_u64 v[174:175], v[128:129], 0, s[8:9]
	v_mfma_f32_16x16x32_bf16 v[96:99], v[160:163], v[192:195], v[96:99]
	ds_read_b128 v[212:215], v249 offset:2048
	v_readfirstlane_b32 s11, v250
	v_add_u32_e32 v250, 0xa000, v251
	v_lshl_add_u64 v[240:241], v[174:175], 0, s[66:67]
	v_mfma_f32_16x16x32_bf16 v[88:91], v[160:163], v[198:201], v[88:91]
	ds_read_b128 v[216:219], v249 offset:4096
	s_mov_b32 m0, s11
	s_mov_b64 s[12:13], 0x22080
	v_readfirstlane_b32 s11, v250
	v_mfma_f32_16x16x32_bf16 v[80:83], v[160:163], v[204:207], v[80:83]
	ds_read_b128 v[220:223], v249 offset:6144
	v_add_u32_e32 v250, 0xc000, v251
	global_load_lds_dwordx4 v[240:241], off
	v_lshl_add_u64 v[240:241], v[174:175], 0, s[12:13]
	v_mfma_f32_16x16x32_bf16 v[72:75], v[178:181], v[186:189], v[72:75]
	s_mov_b32 m0, s11
	s_mov_b64 s[12:13], 0x44080
	v_readfirstlane_b32 s11, v250
	v_mfma_f32_16x16x32_bf16 v[64:67], v[178:181], v[192:195], v[64:67]
	v_add_u32_e32 v251, 0xe000, v251
	global_load_lds_dwordx4 v[240:241], off
	v_lshl_add_u64 v[240:241], v[174:175], 0, s[12:13]
	v_mfma_f32_16x16x32_bf16 v[56:59], v[178:181], v[198:201], v[56:59]
	s_mov_b32 m0, s11
	s_mov_b64 s[12:13], 0x66080
	v_readfirstlane_b32 s11, v251
	v_mfma_f32_16x16x32_bf16 v[48:51], v[178:181], v[204:207], v[48:51]
	global_load_lds_dwordx4 v[240:241], off
	v_lshl_add_u64 v[174:175], v[174:175], 0, s[12:13]
	s_mov_b32 m0, s11
	v_mfma_f32_16x16x32_bf16 v[40:43], v[182:185], v[186:189], v[40:43]
	global_load_lds_dwordx4 v[174:175], off
	v_mfma_f32_16x16x32_bf16 v[32:35], v[182:185], v[192:195], v[32:35]
	v_mfma_f32_16x16x32_bf16 v[24:27], v[182:185], v[198:201], v[24:27]
	v_mfma_f32_16x16x32_bf16 v[16:19], v[182:185], v[204:207], v[16:19]
	s_waitcnt lgkmcnt(4)
	v_mfma_f32_16x16x32_bf16 v[100:103], v[156:159], v[224:227], v[100:103]
	v_mfma_f32_16x16x32_bf16 v[92:95], v[156:159], v[228:231], v[92:95]
	v_mfma_f32_16x16x32_bf16 v[84:87], v[156:159], v[232:235], v[84:87]
	ds_read_b128 v[186:189], v248 offset:32768
	v_mfma_f32_16x16x32_bf16 v[76:79], v[156:159], v[236:239], v[76:79]
	ds_read_b128 v[192:195], v248 offset:34816
	v_mfma_f32_16x16x32_bf16 v[68:71], v[160:163], v[224:227], v[68:71]
	ds_read_b128 v[198:201], v248 offset:36864
	v_mfma_f32_16x16x32_bf16 v[60:63], v[160:163], v[228:231], v[60:63]
	ds_read_b128 v[204:207], v248 offset:38912
	v_mfma_f32_16x16x32_bf16 v[52:55], v[160:163], v[232:235], v[52:55]
	v_mfma_f32_16x16x32_bf16 v[44:47], v[160:163], v[236:239], v[44:47]
	v_mfma_f32_16x16x32_bf16 v[36:39], v[178:181], v[224:227], v[36:39]
	v_mfma_f32_16x16x32_bf16 v[28:31], v[178:181], v[228:231], v[28:31]
	v_mfma_f32_16x16x32_bf16 v[20:23], v[178:181], v[232:235], v[20:23]
	v_mfma_f32_16x16x32_bf16 v[12:15], v[178:181], v[236:239], v[12:15]
	v_mfma_f32_16x16x32_bf16 v[8:11], v[182:185], v[224:227], v[8:11]
	v_mfma_f32_16x16x32_bf16 v[4:7], v[182:185], v[228:231], v[4:7]
	v_mfma_f32_16x16x32_bf16 v[0:3], v[182:185], v[232:235], v[0:3]
	v_mfma_f32_16x16x32_bf16 v[108:111], v[182:185], v[236:239], v[108:111]
	s_waitcnt lgkmcnt(0)
	v_mfma_f32_16x16x32_bf16 v[124:127], v[208:211], v[186:189], v[124:127]
	ds_read_b128 v[224:227], v248 offset:40960
	v_mfma_f32_16x16x32_bf16 v[120:123], v[208:211], v[192:195], v[120:123]
	ds_read_b128 v[228:231], v248 offset:43008
	v_mfma_f32_16x16x32_bf16 v[116:119], v[208:211], v[198:201], v[116:119]
	ds_read_b128 v[232:235], v248 offset:45056
	v_mfma_f32_16x16x32_bf16 v[112:115], v[208:211], v[204:207], v[112:115]
	ds_read_b128 v[236:239], v248 offset:47104
	v_mfma_f32_16x16x32_bf16 v[104:107], v[212:215], v[186:189], v[104:107]
	v_mfma_f32_16x16x32_bf16 v[96:99], v[212:215], v[192:195], v[96:99]
	v_mfma_f32_16x16x32_bf16 v[88:91], v[212:215], v[198:201], v[88:91]
	v_mfma_f32_16x16x32_bf16 v[80:83], v[212:215], v[204:207], v[80:83]
	v_mfma_f32_16x16x32_bf16 v[72:75], v[216:219], v[186:189], v[72:75]
	v_mfma_f32_16x16x32_bf16 v[64:67], v[216:219], v[192:195], v[64:67]
	v_mfma_f32_16x16x32_bf16 v[56:59], v[216:219], v[198:201], v[56:59]
	v_mfma_f32_16x16x32_bf16 v[48:51], v[216:219], v[204:207], v[48:51]
	v_mfma_f32_16x16x32_bf16 v[40:43], v[220:223], v[186:189], v[40:43]
	v_mfma_f32_16x16x32_bf16 v[32:35], v[220:223], v[192:195], v[32:35]
	v_mfma_f32_16x16x32_bf16 v[24:27], v[220:223], v[198:201], v[24:27]
	v_mfma_f32_16x16x32_bf16 v[16:19], v[220:223], v[204:207], v[16:19]
	s_waitcnt lgkmcnt(0)
	v_mfma_f32_16x16x32_bf16 v[100:103], v[208:211], v[224:227], v[100:103]
	v_mfma_f32_16x16x32_bf16 v[92:95], v[208:211], v[228:231], v[92:95]
	v_mfma_f32_16x16x32_bf16 v[84:87], v[208:211], v[232:235], v[84:87]
	v_mfma_f32_16x16x32_bf16 v[76:79], v[208:211], v[236:239], v[76:79]
	v_mfma_f32_16x16x32_bf16 v[68:71], v[212:215], v[224:227], v[68:71]
	v_mfma_f32_16x16x32_bf16 v[60:63], v[212:215], v[228:231], v[60:63]
	v_mfma_f32_16x16x32_bf16 v[52:55], v[212:215], v[232:235], v[52:55]
	v_mfma_f32_16x16x32_bf16 v[44:47], v[212:215], v[236:239], v[44:47]
	v_mfma_f32_16x16x32_bf16 v[36:39], v[216:219], v[224:227], v[36:39]
	v_mfma_f32_16x16x32_bf16 v[28:31], v[216:219], v[228:231], v[28:31]
	v_mfma_f32_16x16x32_bf16 v[20:23], v[216:219], v[232:235], v[20:23]
	v_mfma_f32_16x16x32_bf16 v[12:15], v[216:219], v[236:239], v[12:15]
	s_add_u32 s8, s8, 0x80
	s_addc_u32 s9, s9, 0
	s_cmpk_eq_i32 s8, 0x780
	s_mov_b32 s0, s1
	v_mfma_f32_16x16x32_bf16 v[8:11], v[220:223], v[224:227], v[8:11]
	v_mfma_f32_16x16x32_bf16 v[4:7], v[220:223], v[228:231], v[4:7]
	v_mfma_f32_16x16x32_bf16 v[0:3], v[220:223], v[232:235], v[0:3]
	v_mfma_f32_16x16x32_bf16 v[108:111], v[220:223], v[236:239], v[108:111]
	s_cbranch_scc0 .LBB0_212
	s_add_i32 s0, 0, 0x10000
	v_add_u32_e32 v144, s0, v154
	v_add_u32_e32 v162, s0, v153
	v_add_u32_e32 v145, v144, v151
	v_add_u32_e32 v151, v162, v151
	s_waitcnt vmcnt(0)
	s_barrier
	ds_read_b128 v[128:131], v145 offset:38912
	ds_read_b128 v[132:135], v145 offset:36864
	ds_read_b128 v[154:157], v145 offset:34816
	ds_read_b128 v[158:161], v145 offset:32768
	ds_read_b128 v[178:181], v151 offset:6144
	ds_read_b128 v[182:185], v151 offset:4096
	ds_read_b128 v[186:189], v151 offset:2048
	ds_read_b128 v[204:207], v151
	s_waitcnt lgkmcnt(0)
	v_mfma_f32_16x16x32_bf16 v[124:127], v[204:207], v[158:161], v[124:127]
	v_mfma_f32_16x16x32_bf16 v[120:123], v[204:207], v[154:157], v[120:123]
	v_mfma_f32_16x16x32_bf16 v[116:119], v[204:207], v[132:135], v[116:119]
	v_mfma_f32_16x16x32_bf16 v[112:115], v[204:207], v[128:131], v[112:115]
	v_mfma_f32_16x16x32_bf16 v[104:107], v[186:189], v[158:161], v[104:107]
	v_mfma_f32_16x16x32_bf16 v[72:75], v[182:185], v[158:161], v[72:75]
	v_mfma_f32_16x16x32_bf16 v[64:67], v[182:185], v[154:157], v[64:67]
	v_mfma_f32_16x16x32_bf16 v[56:59], v[182:185], v[132:135], v[56:59]
	v_mfma_f32_16x16x32_bf16 v[48:51], v[182:185], v[128:131], v[48:51]
	v_mfma_f32_16x16x32_bf16 v[208:211], v[186:189], v[154:157], v[96:99]
	v_mfma_f32_16x16x32_bf16 v[212:215], v[186:189], v[132:135], v[88:91]
	v_mfma_f32_16x16x32_bf16 v[216:219], v[186:189], v[128:131], v[80:83]
	v_mfma_f32_16x16x32_bf16 v[158:161], v[178:181], v[158:161], v[40:43]
	v_mfma_f32_16x16x32_bf16 v[152:155], v[178:181], v[154:157], v[32:35]
	v_mfma_f32_16x16x32_bf16 v[132:135], v[178:181], v[132:135], v[24:27]
	v_mfma_f32_16x16x32_bf16 v[128:131], v[178:181], v[128:131], v[16:19]
	s_nop 2
	ds_read_b128 v[16:19], v145 offset:40960
	ds_read_b128 v[24:27], v145 offset:43008
	ds_read_b128 v[32:35], v145 offset:45056
	ds_read_b128 v[40:43], v145 offset:47104
	s_waitcnt lgkmcnt(0)
	v_mfma_f32_16x16x32_bf16 v[100:103], v[204:207], v[16:19], v[100:103]
	v_mfma_f32_16x16x32_bf16 v[92:95], v[204:207], v[24:27], v[92:95]
	v_mfma_f32_16x16x32_bf16 v[220:223], v[204:207], v[32:35], v[84:87]
	v_mfma_f32_16x16x32_bf16 v[76:79], v[204:207], v[40:43], v[76:79]
	v_mfma_f32_16x16x32_bf16 v[68:71], v[186:189], v[16:19], v[68:71]
	v_mfma_f32_16x16x32_bf16 v[60:63], v[186:189], v[24:27], v[60:63]
	v_mfma_f32_16x16x32_bf16 v[204:207], v[186:189], v[32:35], v[52:55]
	v_mfma_f32_16x16x32_bf16 v[44:47], v[186:189], v[40:43], v[44:47]
	v_mfma_f32_16x16x32_bf16 v[186:189], v[182:185], v[16:19], v[36:39]
	v_mfma_f32_16x16x32_bf16 v[224:227], v[182:185], v[24:27], v[28:31]
	v_mfma_f32_16x16x32_bf16 v[228:231], v[182:185], v[32:35], v[20:23]
	v_mfma_f32_16x16x32_bf16 v[182:185], v[182:185], v[40:43], v[12:15]
	v_mfma_f32_16x16x32_bf16 v[232:235], v[178:181], v[16:19], v[8:11]
	v_mfma_f32_16x16x32_bf16 v[236:239], v[178:181], v[24:27], v[4:7]
	v_mfma_f32_16x16x32_bf16 v[240:243], v[178:181], v[32:35], v[0:3]
	v_mfma_f32_16x16x32_bf16 v[244:247], v[178:181], v[40:43], v[108:111]
	s_nop 1
	v_add_u32_e32 v0, v162, v150
	v_add_u32_e32 v144, v144, v150
	ds_read_b128 v[108:111], v0
	ds_read_b128 v[178:181], v0 offset:2048
	ds_read_b128 v[248:251], v0 offset:4096
	ds_read_b128 v[192:195], v0 offset:6144
	ds_read_b128 v[0:3], v144 offset:32768
	ds_read_b128 v[4:7], v144 offset:34816
	ds_read_b128 v[198:201], v144 offset:36864
	ds_read_b128 v[162:165], v144 offset:38912
	s_waitcnt lgkmcnt(0)
	v_mfma_f32_16x16x32_bf16 v[88:91], v[108:111], v[0:3], v[124:127]
	v_mfma_f32_16x16x32_bf16 v[96:99], v[108:111], v[4:7], v[120:123]
	v_mfma_f32_16x16x32_bf16 v[80:83], v[108:111], v[198:201], v[116:119]
	v_mfma_f32_16x16x32_bf16 v[84:87], v[108:111], v[162:165], v[112:115]
	v_mfma_f32_16x16x32_bf16 v[40:43], v[178:181], v[0:3], v[104:107]
	v_mfma_f32_16x16x32_bf16 v[52:55], v[178:181], v[4:7], v[208:211]
	v_mfma_f32_16x16x32_bf16 v[32:35], v[178:181], v[198:201], v[212:215]
	v_mfma_f32_16x16x32_bf16 v[36:39], v[178:181], v[162:165], v[216:219]
	v_mfma_f32_16x16x32_bf16 v[24:27], v[248:251], v[0:3], v[72:75]
	v_mfma_f32_16x16x32_bf16 v[28:31], v[248:251], v[4:7], v[64:67]
	v_mfma_f32_16x16x32_bf16 v[16:19], v[248:251], v[198:201], v[56:59]
	v_mfma_f32_16x16x32_bf16 v[20:23], v[248:251], v[162:165], v[48:51]
	v_mfma_f32_16x16x32_bf16 v[8:11], v[192:195], v[0:3], v[158:161]
	v_mfma_f32_16x16x32_bf16 v[12:15], v[192:195], v[4:7], v[152:155]
	v_mfma_f32_16x16x32_bf16 v[0:3], v[192:195], v[198:201], v[132:135]
	v_mfma_f32_16x16x32_bf16 v[4:7], v[192:195], v[162:165], v[128:131]
	ds_read_b128 v[48:51], v144 offset:40960
	ds_read_b128 v[64:67], v144 offset:43008
	s_nop 0
	ds_read_b128 v[128:131], v144 offset:45056
	ds_read_b128 v[132:135], v144 offset:47104
	s_waitcnt lgkmcnt(0)
	v_mfma_f32_16x16x32_bf16 v[104:107], v[178:181], v[48:51], v[68:71]
	v_cmp_ne_u32_e64 s[8:9], 0, v146
	v_cmp_eq_u32_e32 vcc, 0, v146
	s_waitcnt vmcnt(0)
	v_lshl_or_b32 v68, v148, 2, v149
	v_lshl_add_u32 v69, v147, 2, 0
	v_mfma_f32_16x16x32_bf16 v[120:123], v[108:111], v[48:51], v[100:103]
	s_barrier
	v_mfma_f32_16x16x32_bf16 v[124:127], v[108:111], v[64:67], v[92:95]
	v_mfma_f32_16x16x32_bf16 v[112:115], v[108:111], v[128:131], v[220:223]
	v_mfma_f32_16x16x32_bf16 v[116:119], v[108:111], v[132:135], v[76:79]
	v_mfma_f32_16x16x32_bf16 v[108:111], v[178:181], v[64:67], v[60:63]
	v_mfma_f32_16x16x32_bf16 v[92:95], v[178:181], v[128:131], v[204:207]
	v_mfma_f32_16x16x32_bf16 v[100:103], v[178:181], v[132:135], v[44:47]
	v_mfma_f32_16x16x32_bf16 v[56:59], v[248:251], v[48:51], v[186:189]
	v_mfma_f32_16x16x32_bf16 v[60:63], v[248:251], v[64:67], v[224:227]
	v_mfma_f32_16x16x32_bf16 v[44:47], v[248:251], v[128:131], v[228:231]
	v_mfma_f32_16x16x32_bf16 v[72:75], v[248:251], v[132:135], v[182:185]
	v_mfma_f32_16x16x32_bf16 v[48:51], v[192:195], v[48:51], v[232:235]
	s_nop 1
	v_lshl_add_u32 v182, v68, 9, v69
	v_add_u32_e32 v183, 0x400, v182
	v_add_u32_e32 v181, 0x2000, v182
	v_mfma_f32_16x16x32_bf16 v[64:67], v[192:195], v[64:67], v[236:239]
	v_add_u32_e32 v180, 0x2400, v182
	v_add_u32_e32 v179, 0x4000, v182
	v_add_u32_e32 v178, 0x4400, v182
	v_mfma_f32_16x16x32_bf16 v[68:71], v[192:195], v[128:131], v[240:243]
	v_add_u32_e32 v175, 0x6000, v182
	v_add_u32_e32 v174, 0x6400, v182
	v_mfma_f32_16x16x32_bf16 v[76:79], v[192:195], v[132:135], v[244:247]
	s_and_saveexec_b64 s[0:1], vcc
	s_cbranch_execz .LBB0_215
	ds_write2_b32 v182, v88, v96 offset1:16
	ds_write2_b32 v182, v89, v97 offset0:128 offset1:144
	ds_write2_b32 v183, v90, v98 offset1:16
	ds_write2_b32 v183, v91, v99 offset0:128 offset1:144
	ds_write2_b32 v182, v80, v84 offset0:32 offset1:48
	ds_write2_b32 v182, v81, v85 offset0:160 offset1:176
	ds_write2_b32 v183, v82, v86 offset0:32 offset1:48
	ds_write2_b32 v183, v83, v87 offset0:160 offset1:176
	ds_write2_b32 v182, v120, v124 offset0:64 offset1:80
	ds_write2_b32 v182, v121, v125 offset0:192 offset1:208
	ds_write2_b32 v183, v122, v126 offset0:64 offset1:80
	ds_write2_b32 v183, v123, v127 offset0:192 offset1:208
	ds_write2_b32 v182, v112, v116 offset0:96 offset1:112
	ds_write2_b32 v182, v113, v117 offset0:224 offset1:240
	ds_write2_b32 v183, v114, v118 offset0:96 offset1:112
	ds_write2_b32 v183, v115, v119 offset0:224 offset1:240
	ds_write2_b32 v181, v40, v52 offset1:16
	ds_write2_b32 v181, v41, v53 offset0:128 offset1:144
	ds_write2_b32 v180, v42, v54 offset1:16
	ds_write2_b32 v180, v43, v55 offset0:128 offset1:144
	ds_write2_b32 v181, v32, v36 offset0:32 offset1:48
	ds_write2_b32 v181, v33, v37 offset0:160 offset1:176
	ds_write2_b32 v180, v34, v38 offset0:32 offset1:48
	ds_write2_b32 v180, v35, v39 offset0:160 offset1:176
	ds_write2_b32 v181, v104, v108 offset0:64 offset1:80
	ds_write2_b32 v181, v105, v109 offset0:192 offset1:208
	ds_write2_b32 v180, v106, v110 offset0:64 offset1:80
	ds_write2_b32 v180, v107, v111 offset0:192 offset1:208
	ds_write2_b32 v181, v92, v100 offset0:96 offset1:112
	ds_write2_b32 v181, v93, v101 offset0:224 offset1:240
	ds_write2_b32 v180, v94, v102 offset0:96 offset1:112
	ds_write2_b32 v180, v95, v103 offset0:224 offset1:240
	ds_write2_b32 v179, v24, v28 offset1:16
	ds_write2_b32 v179, v25, v29 offset0:128 offset1:144
	ds_write2_b32 v178, v26, v30 offset1:16
	ds_write2_b32 v178, v27, v31 offset0:128 offset1:144
	ds_write2_b32 v179, v16, v20 offset0:32 offset1:48
	ds_write2_b32 v179, v17, v21 offset0:160 offset1:176
	ds_write2_b32 v178, v18, v22 offset0:32 offset1:48
	ds_write2_b32 v178, v19, v23 offset0:160 offset1:176
	ds_write2_b32 v179, v56, v60 offset0:64 offset1:80
	ds_write2_b32 v179, v57, v61 offset0:192 offset1:208
	ds_write2_b32 v178, v58, v62 offset0:64 offset1:80
	ds_write2_b32 v178, v59, v63 offset0:192 offset1:208
	ds_write2_b32 v179, v44, v72 offset0:96 offset1:112
	ds_write2_b32 v179, v45, v73 offset0:224 offset1:240
	ds_write2_b32 v178, v46, v74 offset0:96 offset1:112
	ds_write2_b32 v178, v47, v75 offset0:224 offset1:240
	ds_write2_b32 v175, v8, v12 offset1:16
	ds_write2_b32 v175, v9, v13 offset0:128 offset1:144
	ds_write2_b32 v174, v10, v14 offset1:16
	ds_write2_b32 v174, v11, v15 offset0:128 offset1:144
	ds_write2_b32 v175, v0, v4 offset0:32 offset1:48
	ds_write2_b32 v175, v1, v5 offset0:160 offset1:176
	ds_write2_b32 v174, v2, v6 offset0:32 offset1:48
	ds_write2_b32 v174, v3, v7 offset0:160 offset1:176
	ds_write2_b32 v175, v48, v64 offset0:64 offset1:80
	ds_write2_b32 v175, v49, v65 offset0:192 offset1:208
	ds_write2_b32 v174, v50, v66 offset0:64 offset1:80
	ds_write2_b32 v174, v51, v67 offset0:192 offset1:208
	ds_write2_b32 v175, v68, v76 offset0:96 offset1:112
	ds_write2_b32 v175, v69, v77 offset0:224 offset1:240
	ds_write2_b32 v174, v70, v78 offset0:96 offset1:112
	ds_write2_b32 v174, v71, v79 offset0:224 offset1:240

.LBB0_659:
	s_add_i32 s1, s0, 0x10000
	s_and_b32 s11, s1, 0x10000
	s_waitcnt vmcnt(0)
	s_barrier
	s_and_b32 s0, s0, 0x10000
	s_add_i32 s0, s0, 0
	v_add_u32_e32 v151, s0, v149
	v_add_u32_e32 v164, v151, v147
	ds_read_b128 v[152:155], v164
	ds_read_b128 v[156:159], v164 offset:2048
	ds_read_b128 v[160:163], v164 offset:4096
	ds_read_b128 v[164:167], v164 offset:6144
	v_add_u32_e32 v251, v151, v146
	v_add_u32_e32 v176, s0, v148
	v_add_u32_e32 v186, v176, v147
	ds_read_b128 v[168:171], v186 offset:32768
	ds_read_b128 v[172:175], v186 offset:34816
	ds_read_b128 v[178:181], v186 offset:36864
	ds_read_b128 v[182:185], v186 offset:38912
	v_add_u32_e32 v250, v176, v146
	v_add_u32_e32 v254, s11, v150
	v_add_u32_e32 v228, 0x2000, v254
	v_readfirstlane_b32 s11, v254
	v_lshl_add_u64 v[188:189], v[128:129], 0, s[2:3]
	s_mov_b32 m0, s11
	v_readfirstlane_b32 s11, v228
	v_add_u32_e32 v228, 0x4000, v254
	global_load_lds_dwordx4 v[188:189], off
	v_lshl_add_u64 v[188:189], v[130:131], 0, s[2:3]
	s_mov_b32 m0, s11
	s_waitcnt lgkmcnt(0)
	v_mfma_f32_16x16x32_bf16 v[124:127], v[152:155], v[168:171], v[124:127]
	ds_read_b128 v[212:215], v186 offset:40960
	v_mfma_f32_16x16x32_bf16 v[120:123], v[152:155], v[172:175], v[120:123]
	ds_read_b128 v[216:219], v186 offset:43008
	v_readfirstlane_b32 s11, v228
	v_add_u32_e32 v228, 0x6000, v254
	global_load_lds_dwordx4 v[188:189], off
	v_mfma_f32_16x16x32_bf16 v[116:119], v[152:155], v[178:181], v[116:119]
	ds_read_b128 v[220:223], v186 offset:45056
	v_lshl_add_u64 v[188:189], v[132:133], 0, s[2:3]
	s_mov_b32 m0, s11
	v_readfirstlane_b32 s11, v228
	v_mfma_f32_16x16x32_bf16 v[112:115], v[152:155], v[182:185], v[112:115]
	ds_read_b128 v[224:227], v186 offset:47104
	global_load_lds_dwordx4 v[188:189], off
	v_lshl_add_u64 v[188:189], v[134:135], 0, s[2:3]
	s_mov_b32 m0, s11
	v_mfma_f32_16x16x32_bf16 v[104:107], v[156:159], v[168:171], v[104:107]
	ds_read_b128 v[192:195], v251
	v_add_u32_e32 v253, 0x8000, v254
	global_load_lds_dwordx4 v[188:189], off
	v_lshl_add_u64 v[188:189], v[136:137], 0, s[2:3]
	v_mfma_f32_16x16x32_bf16 v[96:99], v[156:159], v[172:175], v[96:99]
	ds_read_b128 v[198:201], v251 offset:2048
	s_mov_b64 s[18:19], 0x550080
	v_readfirstlane_b32 s11, v253
	v_add_u32_e32 v253, 0xa000, v254
	v_mfma_f32_16x16x32_bf16 v[88:91], v[156:159], v[178:181], v[88:91]
	ds_read_b128 v[204:207], v251 offset:4096
	v_lshl_add_u64 v[228:229], v[188:189], 0, s[18:19]
	s_mov_b32 m0, s11
	s_mov_b64 s[18:19], 0x572080
	v_mfma_f32_16x16x32_bf16 v[80:83], v[156:159], v[182:185], v[80:83]
	ds_read_b128 v[208:211], v251 offset:6144
	v_readfirstlane_b32 s11, v253
	v_add_u32_e32 v253, 0xc000, v254
	global_load_lds_dwordx4 v[228:229], off
	v_mfma_f32_16x16x32_bf16 v[72:75], v[160:163], v[168:171], v[72:75]
	v_lshl_add_u64 v[228:229], v[188:189], 0, s[18:19]
	s_mov_b32 m0, s11
	s_mov_b64 s[18:19], 0x594080
	v_mfma_f32_16x16x32_bf16 v[64:67], v[160:163], v[172:175], v[64:67]
	v_readfirstlane_b32 s11, v253
	v_add_u32_e32 v254, 0xe000, v254
	global_load_lds_dwordx4 v[228:229], off
	v_mfma_f32_16x16x32_bf16 v[56:59], v[160:163], v[178:181], v[56:59]
	v_lshl_add_u64 v[228:229], v[188:189], 0, s[18:19]
	s_mov_b32 m0, s11
	s_mov_b64 s[18:19], 0x5b6080
	v_mfma_f32_16x16x32_bf16 v[48:51], v[160:163], v[182:185], v[48:51]
	v_readfirstlane_b32 s11, v254
	global_load_lds_dwordx4 v[228:229], off
	v_lshl_add_u64 v[188:189], v[188:189], 0, s[18:19]
	v_mfma_f32_16x16x32_bf16 v[40:43], v[164:167], v[168:171], v[40:43]
	s_mov_b32 m0, s11
	global_load_lds_dwordx4 v[188:189], off
	v_mfma_f32_16x16x32_bf16 v[32:35], v[164:167], v[172:175], v[32:35]
	v_mfma_f32_16x16x32_bf16 v[24:27], v[164:167], v[178:181], v[24:27]
	v_mfma_f32_16x16x32_bf16 v[16:19], v[164:167], v[182:185], v[16:19]
	s_waitcnt lgkmcnt(4)
	v_mfma_f32_16x16x32_bf16 v[100:103], v[152:155], v[212:215], v[100:103]
	v_mfma_f32_16x16x32_bf16 v[92:95], v[152:155], v[216:219], v[92:95]
	v_mfma_f32_16x16x32_bf16 v[84:87], v[152:155], v[220:223], v[84:87]
	ds_read_b128 v[168:171], v250 offset:32768
	v_mfma_f32_16x16x32_bf16 v[76:79], v[152:155], v[224:227], v[76:79]
	ds_read_b128 v[172:175], v250 offset:34816
	v_mfma_f32_16x16x32_bf16 v[68:71], v[156:159], v[212:215], v[68:71]
	ds_read_b128 v[178:181], v250 offset:36864
	v_mfma_f32_16x16x32_bf16 v[60:63], v[156:159], v[216:219], v[60:63]
	ds_read_b128 v[182:185], v250 offset:38912
	v_mfma_f32_16x16x32_bf16 v[52:55], v[156:159], v[220:223], v[52:55]
	v_mfma_f32_16x16x32_bf16 v[44:47], v[156:159], v[224:227], v[44:47]
	v_mfma_f32_16x16x32_bf16 v[36:39], v[160:163], v[212:215], v[36:39]
	v_mfma_f32_16x16x32_bf16 v[28:31], v[160:163], v[216:219], v[28:31]
	v_mfma_f32_16x16x32_bf16 v[20:23], v[160:163], v[220:223], v[20:23]
	v_mfma_f32_16x16x32_bf16 v[12:15], v[160:163], v[224:227], v[12:15]
	v_mfma_f32_16x16x32_bf16 v[8:11], v[164:167], v[212:215], v[8:11]
	v_mfma_f32_16x16x32_bf16 v[4:7], v[164:167], v[216:219], v[4:7]
	v_mfma_f32_16x16x32_bf16 v[0:3], v[164:167], v[220:223], v[0:3]
	v_mfma_f32_16x16x32_bf16 v[108:111], v[164:167], v[224:227], v[108:111]
	s_waitcnt lgkmcnt(0)
	v_mfma_f32_16x16x32_bf16 v[124:127], v[192:195], v[168:171], v[124:127]
	ds_read_b128 v[212:215], v250 offset:40960
	v_mfma_f32_16x16x32_bf16 v[120:123], v[192:195], v[172:175], v[120:123]
	ds_read_b128 v[216:219], v250 offset:43008
	v_mfma_f32_16x16x32_bf16 v[116:119], v[192:195], v[178:181], v[116:119]
	ds_read_b128 v[220:223], v250 offset:45056
	v_mfma_f32_16x16x32_bf16 v[112:115], v[192:195], v[182:185], v[112:115]
	ds_read_b128 v[224:227], v250 offset:47104
	v_mfma_f32_16x16x32_bf16 v[104:107], v[198:201], v[168:171], v[104:107]
	v_mfma_f32_16x16x32_bf16 v[96:99], v[198:201], v[172:175], v[96:99]
	v_mfma_f32_16x16x32_bf16 v[88:91], v[198:201], v[178:181], v[88:91]
	v_mfma_f32_16x16x32_bf16 v[80:83], v[198:201], v[182:185], v[80:83]
	v_mfma_f32_16x16x32_bf16 v[72:75], v[204:207], v[168:171], v[72:75]
	v_mfma_f32_16x16x32_bf16 v[64:67], v[204:207], v[172:175], v[64:67]
	v_mfma_f32_16x16x32_bf16 v[56:59], v[204:207], v[178:181], v[56:59]
	v_mfma_f32_16x16x32_bf16 v[48:51], v[204:207], v[182:185], v[48:51]
	v_mfma_f32_16x16x32_bf16 v[40:43], v[208:211], v[168:171], v[40:43]
	v_mfma_f32_16x16x32_bf16 v[32:35], v[208:211], v[172:175], v[32:35]
	v_mfma_f32_16x16x32_bf16 v[24:27], v[208:211], v[178:181], v[24:27]
	v_mfma_f32_16x16x32_bf16 v[16:19], v[208:211], v[182:185], v[16:19]
	s_waitcnt lgkmcnt(0)
	v_mfma_f32_16x16x32_bf16 v[100:103], v[192:195], v[212:215], v[100:103]
	v_mfma_f32_16x16x32_bf16 v[92:95], v[192:195], v[216:219], v[92:95]
	v_mfma_f32_16x16x32_bf16 v[84:87], v[192:195], v[220:223], v[84:87]
	v_mfma_f32_16x16x32_bf16 v[76:79], v[192:195], v[224:227], v[76:79]
	v_mfma_f32_16x16x32_bf16 v[68:71], v[198:201], v[212:215], v[68:71]
	v_mfma_f32_16x16x32_bf16 v[60:63], v[198:201], v[216:219], v[60:63]
	v_mfma_f32_16x16x32_bf16 v[52:55], v[198:201], v[220:223], v[52:55]
	v_mfma_f32_16x16x32_bf16 v[44:47], v[198:201], v[224:227], v[44:47]
	v_mfma_f32_16x16x32_bf16 v[36:39], v[204:207], v[212:215], v[36:39]
	v_mfma_f32_16x16x32_bf16 v[28:31], v[204:207], v[216:219], v[28:31]
	v_mfma_f32_16x16x32_bf16 v[20:23], v[204:207], v[220:223], v[20:23]
	v_mfma_f32_16x16x32_bf16 v[12:15], v[204:207], v[224:227], v[12:15]
	s_add_u32 s2, s2, 0x80
	s_addc_u32 s3, s3, 0
	s_cmpk_eq_i32 s2, 0x780
	s_mov_b32 s0, s1
	v_mfma_f32_16x16x32_bf16 v[8:11], v[208:211], v[212:215], v[8:11]
	v_mfma_f32_16x16x32_bf16 v[4:7], v[208:211], v[216:219], v[4:7]
	v_mfma_f32_16x16x32_bf16 v[0:3], v[208:211], v[220:223], v[0:3]
	v_mfma_f32_16x16x32_bf16 v[108:111], v[208:211], v[224:227], v[108:111]
	s_cbranch_scc0 .LBB0_659
	s_add_i32 s0, 0, 0x10000
	v_add_u32_e32 v136, s0, v149
	v_add_u32_e32 v137, v136, v147
	s_waitcnt vmcnt(0)
	s_barrier
	ds_read_b128 v[128:131], v137
	ds_read_b128 v[132:135], v137 offset:2048
	ds_read_b128 v[150:153], v137 offset:4096
	ds_read_b128 v[154:157], v137 offset:6144
	v_add_u32_e32 v137, s0, v148
	v_add_u32_e32 v147, v137, v147
	ds_read_b128 v[158:161], v147 offset:32768
	ds_read_b128 v[162:165], v147 offset:34816
	ds_read_b128 v[166:169], v147 offset:36864
	ds_read_b128 v[170:173], v147 offset:38912
	s_waitcnt lgkmcnt(0)
	v_mfma_f32_16x16x32_bf16 v[124:127], v[128:131], v[158:161], v[124:127]
	v_mfma_f32_16x16x32_bf16 v[120:123], v[128:131], v[162:165], v[120:123]
	v_mfma_f32_16x16x32_bf16 v[116:119], v[128:131], v[166:169], v[116:119]
	v_mfma_f32_16x16x32_bf16 v[112:115], v[128:131], v[170:173], v[112:115]
	v_mfma_f32_16x16x32_bf16 v[104:107], v[132:135], v[158:161], v[104:107]
	v_mfma_f32_16x16x32_bf16 v[72:75], v[150:153], v[158:161], v[72:75]
	v_mfma_f32_16x16x32_bf16 v[64:67], v[150:153], v[162:165], v[64:67]
	v_mfma_f32_16x16x32_bf16 v[56:59], v[150:153], v[166:169], v[56:59]
	v_mfma_f32_16x16x32_bf16 v[48:51], v[150:153], v[170:173], v[48:51]
	v_mfma_f32_16x16x32_bf16 v[178:181], v[132:135], v[162:165], v[96:99]
	v_mfma_f32_16x16x32_bf16 v[182:185], v[132:135], v[166:169], v[88:91]
	v_mfma_f32_16x16x32_bf16 v[186:189], v[132:135], v[170:173], v[80:83]
	v_mfma_f32_16x16x32_bf16 v[158:161], v[154:157], v[158:161], v[40:43]
	v_mfma_f32_16x16x32_bf16 v[162:165], v[154:157], v[162:165], v[32:35]
	v_mfma_f32_16x16x32_bf16 v[166:169], v[154:157], v[166:169], v[24:27]
	v_mfma_f32_16x16x32_bf16 v[170:173], v[154:157], v[170:173], v[16:19]
	s_nop 2
	ds_read_b128 v[16:19], v147 offset:40960
	ds_read_b128 v[24:27], v147 offset:43008
	ds_read_b128 v[32:35], v147 offset:45056
	ds_read_b128 v[40:43], v147 offset:47104
	s_waitcnt lgkmcnt(0)
	v_mfma_f32_16x16x32_bf16 v[100:103], v[128:131], v[16:19], v[100:103]
	v_mfma_f32_16x16x32_bf16 v[92:95], v[128:131], v[24:27], v[92:95]
	v_mfma_f32_16x16x32_bf16 v[192:195], v[128:131], v[32:35], v[84:87]
	v_mfma_f32_16x16x32_bf16 v[76:79], v[128:131], v[40:43], v[76:79]
	v_mfma_f32_16x16x32_bf16 v[68:71], v[132:135], v[16:19], v[68:71]
	v_mfma_f32_16x16x32_bf16 v[60:63], v[132:135], v[24:27], v[60:63]
	v_mfma_f32_16x16x32_bf16 v[128:131], v[132:135], v[32:35], v[52:55]
	v_mfma_f32_16x16x32_bf16 v[44:47], v[132:135], v[40:43], v[44:47]
	v_mfma_f32_16x16x32_bf16 v[132:135], v[150:153], v[16:19], v[36:39]
	v_mfma_f32_16x16x32_bf16 v[198:201], v[150:153], v[24:27], v[28:31]
	v_mfma_f32_16x16x32_bf16 v[204:207], v[150:153], v[32:35], v[20:23]
	v_mfma_f32_16x16x32_bf16 v[148:151], v[150:153], v[40:43], v[12:15]
	v_mfma_f32_16x16x32_bf16 v[208:211], v[154:157], v[16:19], v[8:11]
	v_mfma_f32_16x16x32_bf16 v[212:215], v[154:157], v[24:27], v[4:7]
	v_mfma_f32_16x16x32_bf16 v[216:219], v[154:157], v[32:35], v[0:3]
	v_mfma_f32_16x16x32_bf16 v[154:157], v[154:157], v[40:43], v[108:111]
	s_nop 1
	v_add_u32_e32 v0, v136, v146
	v_add_u32_e32 v136, v137, v146
	ds_read_b128 v[108:111], v0
	ds_read_b128 v[220:223], v0 offset:2048
	ds_read_b128 v[224:227], v0 offset:4096
	ds_read_b128 v[228:231], v0 offset:6144
	ds_read_b128 v[0:3], v136 offset:32768
	ds_read_b128 v[4:7], v136 offset:34816
	ds_read_b128 v[232:235], v136 offset:36864
	ds_read_b128 v[236:239], v136 offset:38912
	s_waitcnt lgkmcnt(0)
	v_mfma_f32_16x16x32_bf16 v[88:91], v[108:111], v[0:3], v[124:127]
	v_mfma_f32_16x16x32_bf16 v[96:99], v[108:111], v[4:7], v[120:123]
	v_mfma_f32_16x16x32_bf16 v[80:83], v[108:111], v[232:235], v[116:119]
	v_mfma_f32_16x16x32_bf16 v[84:87], v[108:111], v[236:239], v[112:115]
	v_mfma_f32_16x16x32_bf16 v[40:43], v[220:223], v[0:3], v[104:107]
	v_mfma_f32_16x16x32_bf16 v[52:55], v[220:223], v[4:7], v[178:181]
	v_mfma_f32_16x16x32_bf16 v[32:35], v[220:223], v[232:235], v[182:185]
	v_mfma_f32_16x16x32_bf16 v[36:39], v[220:223], v[236:239], v[186:189]
	v_mfma_f32_16x16x32_bf16 v[24:27], v[224:227], v[0:3], v[72:75]
	v_mfma_f32_16x16x32_bf16 v[28:31], v[224:227], v[4:7], v[64:67]
	v_mfma_f32_16x16x32_bf16 v[16:19], v[224:227], v[232:235], v[56:59]
	v_mfma_f32_16x16x32_bf16 v[20:23], v[224:227], v[236:239], v[48:51]
	v_mfma_f32_16x16x32_bf16 v[8:11], v[228:231], v[0:3], v[158:161]
	v_mfma_f32_16x16x32_bf16 v[12:15], v[228:231], v[4:7], v[162:165]
	v_mfma_f32_16x16x32_bf16 v[0:3], v[228:231], v[232:235], v[166:169]
	v_mfma_f32_16x16x32_bf16 v[4:7], v[228:231], v[236:239], v[170:173]
	ds_read_b128 v[48:51], v136 offset:40960
	ds_read_b128 v[64:67], v136 offset:43008
	ds_read_b128 v[158:161], v136 offset:45056
	ds_read_b128 v[162:165], v136 offset:47104
	s_waitcnt lgkmcnt(0)
	v_mfma_f32_16x16x32_bf16 v[104:107], v[220:223], v[48:51], v[68:71]
	v_cmp_ne_u32_e32 vcc, 0, v138
	v_cmp_eq_u32_e64 s[2:3], 0, v138
	s_waitcnt vmcnt(0)
	v_lshl_or_b32 v68, v140, 2, v141
	v_lshl_add_u32 v69, v139, 2, 0
	v_mfma_f32_16x16x32_bf16 v[120:123], v[108:111], v[48:51], v[100:103]
	v_lshl_add_u32 v152, v68, 9, v69
	v_add_u32_e32 v153, 0x400, v152
	v_add_u32_e32 v147, 0x6000, v152
	v_mfma_f32_16x16x32_bf16 v[124:127], v[108:111], v[64:67], v[92:95]
	v_add_u32_e32 v146, 0x6400, v152
	s_barrier
	v_mfma_f32_16x16x32_bf16 v[112:115], v[108:111], v[158:161], v[192:195]
	v_mfma_f32_16x16x32_bf16 v[116:119], v[108:111], v[162:165], v[76:79]
	v_mfma_f32_16x16x32_bf16 v[108:111], v[220:223], v[64:67], v[60:63]
	v_mfma_f32_16x16x32_bf16 v[92:95], v[220:223], v[158:161], v[128:131]
	v_mfma_f32_16x16x32_bf16 v[100:103], v[220:223], v[162:165], v[44:47]
	v_mfma_f32_16x16x32_bf16 v[56:59], v[224:227], v[48:51], v[132:135]
	v_mfma_f32_16x16x32_bf16 v[60:63], v[224:227], v[64:67], v[198:201]
	v_mfma_f32_16x16x32_bf16 v[44:47], v[224:227], v[158:161], v[204:207]
	v_mfma_f32_16x16x32_bf16 v[72:75], v[224:227], v[162:165], v[148:151]
	v_mfma_f32_16x16x32_bf16 v[48:51], v[228:231], v[48:51], v[208:211]
	s_nop 1
	v_add_u32_e32 v151, 0x2000, v152
	v_add_u32_e32 v150, 0x2400, v152
	v_add_u32_e32 v149, 0x4000, v152
	v_mfma_f32_16x16x32_bf16 v[64:67], v[228:231], v[64:67], v[212:215]
	v_add_u32_e32 v148, 0x4400, v152
	v_mfma_f32_16x16x32_bf16 v[68:71], v[228:231], v[158:161], v[216:219]
	v_mfma_f32_16x16x32_bf16 v[76:79], v[228:231], v[162:165], v[154:157]
	s_and_saveexec_b64 s[0:1], s[2:3]
	s_cbranch_execz .LBB0_662
	ds_write2_b32 v152, v88, v96 offset1:16
	ds_write2_b32 v152, v89, v97 offset0:128 offset1:144
	ds_write2_b32 v153, v90, v98 offset1:16
	ds_write2_b32 v153, v91, v99 offset0:128 offset1:144
	ds_write2_b32 v152, v80, v84 offset0:32 offset1:48
	ds_write2_b32 v152, v81, v85 offset0:160 offset1:176
	ds_write2_b32 v153, v82, v86 offset0:32 offset1:48
	ds_write2_b32 v153, v83, v87 offset0:160 offset1:176
	ds_write2_b32 v152, v120, v124 offset0:64 offset1:80
	ds_write2_b32 v152, v121, v125 offset0:192 offset1:208
	ds_write2_b32 v153, v122, v126 offset0:64 offset1:80
	ds_write2_b32 v153, v123, v127 offset0:192 offset1:208
	ds_write2_b32 v152, v112, v116 offset0:96 offset1:112
	ds_write2_b32 v152, v113, v117 offset0:224 offset1:240
	ds_write2_b32 v153, v114, v118 offset0:96 offset1:112
	ds_write2_b32 v153, v115, v119 offset0:224 offset1:240
	ds_write2_b32 v151, v40, v52 offset1:16
	ds_write2_b32 v151, v41, v53 offset0:128 offset1:144
	ds_write2_b32 v150, v42, v54 offset1:16
	ds_write2_b32 v150, v43, v55 offset0:128 offset1:144
	ds_write2_b32 v151, v32, v36 offset0:32 offset1:48
	ds_write2_b32 v151, v33, v37 offset0:160 offset1:176
	ds_write2_b32 v150, v34, v38 offset0:32 offset1:48
	ds_write2_b32 v150, v35, v39 offset0:160 offset1:176
	ds_write2_b32 v151, v104, v108 offset0:64 offset1:80
	ds_write2_b32 v151, v105, v109 offset0:192 offset1:208
	ds_write2_b32 v150, v106, v110 offset0:64 offset1:80
	ds_write2_b32 v150, v107, v111 offset0:192 offset1:208
	ds_write2_b32 v151, v92, v100 offset0:96 offset1:112
	ds_write2_b32 v151, v93, v101 offset0:224 offset1:240
	ds_write2_b32 v150, v94, v102 offset0:96 offset1:112
	ds_write2_b32 v150, v95, v103 offset0:224 offset1:240
	ds_write2_b32 v149, v24, v28 offset1:16
	ds_write2_b32 v149, v25, v29 offset0:128 offset1:144
	ds_write2_b32 v148, v26, v30 offset1:16
	ds_write2_b32 v148, v27, v31 offset0:128 offset1:144
	ds_write2_b32 v149, v16, v20 offset0:32 offset1:48
	ds_write2_b32 v149, v17, v21 offset0:160 offset1:176
	ds_write2_b32 v148, v18, v22 offset0:32 offset1:48
	ds_write2_b32 v148, v19, v23 offset0:160 offset1:176
	ds_write2_b32 v149, v56, v60 offset0:64 offset1:80
	ds_write2_b32 v149, v57, v61 offset0:192 offset1:208
	ds_write2_b32 v148, v58, v62 offset0:64 offset1:80
	ds_write2_b32 v148, v59, v63 offset0:192 offset1:208
	ds_write2_b32 v149, v44, v72 offset0:96 offset1:112
	ds_write2_b32 v149, v45, v73 offset0:224 offset1:240
	ds_write2_b32 v148, v46, v74 offset0:96 offset1:112
	ds_write2_b32 v148, v47, v75 offset0:224 offset1:240
	ds_write2_b32 v147, v8, v12 offset1:16
	ds_write2_b32 v147, v9, v13 offset0:128 offset1:144
	ds_write2_b32 v146, v10, v14 offset1:16
	ds_write2_b32 v146, v11, v15 offset0:128 offset1:144
	ds_write2_b32 v147, v0, v4 offset0:32 offset1:48
	ds_write2_b32 v147, v1, v5 offset0:160 offset1:176
	ds_write2_b32 v146, v2, v6 offset0:32 offset1:48
	ds_write2_b32 v146, v3, v7 offset0:160 offset1:176
	ds_write2_b32 v147, v48, v64 offset0:64 offset1:80
	ds_write2_b32 v147, v49, v65 offset0:192 offset1:208
	ds_write2_b32 v146, v50, v66 offset0:64 offset1:80
	ds_write2_b32 v146, v51, v67 offset0:192 offset1:208
	ds_write2_b32 v147, v68, v76 offset0:96 offset1:112
	ds_write2_b32 v147, v69, v77 offset0:224 offset1:240
	ds_write2_b32 v146, v70, v78 offset0:96 offset1:112
	ds_write2_b32 v146, v71, v79 offset0:224 offset1:240

.LBB0_1074:
	s_add_i32 s5, s4, 0x10000
	s_and_b32 s40, s5, 0x10000
	s_waitcnt vmcnt(0)
	s_barrier
	s_and_b32 s4, s4, 0x10000
	s_add_i32 s4, s4, 0
	v_add_u32_e32 v147, s4, v144
	v_add_u32_e32 v160, v147, v143
	ds_read_b128 v[148:151], v160
	ds_read_b128 v[152:155], v160 offset:2048
	ds_read_b128 v[156:159], v160 offset:4096
	ds_read_b128 v[170:173], v160 offset:6144
	v_add_u32_e32 v251, v147, v142
	v_add_u32_e32 v160, s4, v145
	v_add_u32_e32 v161, v160, v143
	ds_read_b128 v[178:181], v161 offset:32768
	ds_read_b128 v[182:185], v161 offset:34816
	ds_read_b128 v[186:189], v161 offset:36864
	ds_read_b128 v[192:195], v161 offset:38912
	v_add_u32_e32 v250, v160, v142
	v_add_u32_e32 v254, s40, v146
	v_add_u32_e32 v232, 0x2000, v254
	v_readfirstlane_b32 s40, v254
	v_lshl_add_u64 v[174:175], v[136:137], 0, s[2:3]
	s_mov_b32 m0, s40
	v_readfirstlane_b32 s40, v232
	v_add_u32_e32 v232, 0x4000, v254
	global_load_lds_dwordx4 v[174:175], off
	v_lshl_add_u64 v[174:175], v[134:135], 0, s[2:3]
	s_mov_b32 m0, s40
	s_waitcnt lgkmcnt(0)
	v_mfma_f32_16x16x32_bf16 v[124:127], v[148:151], v[178:181], v[124:127]
	ds_read_b128 v[216:219], v161 offset:40960
	v_mfma_f32_16x16x32_bf16 v[120:123], v[148:151], v[182:185], v[120:123]
	ds_read_b128 v[220:223], v161 offset:43008
	v_readfirstlane_b32 s40, v232
	v_add_u32_e32 v232, 0x6000, v254
	global_load_lds_dwordx4 v[174:175], off
	v_mfma_f32_16x16x32_bf16 v[116:119], v[148:151], v[186:189], v[116:119]
	ds_read_b128 v[224:227], v161 offset:45056
	v_lshl_add_u64 v[174:175], v[132:133], 0, s[2:3]
	s_mov_b32 m0, s40
	v_readfirstlane_b32 s40, v232
	v_mfma_f32_16x16x32_bf16 v[112:115], v[148:151], v[192:195], v[112:115]
	ds_read_b128 v[228:231], v161 offset:47104
	global_load_lds_dwordx4 v[174:175], off
	v_lshl_add_u64 v[174:175], v[130:131], 0, s[2:3]
	s_mov_b32 m0, s40
	v_mfma_f32_16x16x32_bf16 v[104:107], v[152:155], v[178:181], v[104:107]
	ds_read_b128 v[198:201], v251
	s_mov_b64 s[40:41], 0x770080
	global_load_lds_dwordx4 v[174:175], off
	v_lshl_add_u64 v[174:175], v[128:129], 0, s[2:3]
	v_mfma_f32_16x16x32_bf16 v[96:99], v[152:155], v[182:185], v[96:99]
	ds_read_b128 v[204:207], v251 offset:2048
	v_add_u32_e32 v253, 0x8000, v254
	v_lshl_add_u64 v[232:233], v[174:175], 0, s[40:41]
	v_readfirstlane_b32 s40, v253
	v_mfma_f32_16x16x32_bf16 v[88:91], v[152:155], v[186:189], v[88:91]
	ds_read_b128 v[208:211], v251 offset:4096
	s_mov_b32 m0, s40
	s_mov_b64 s[40:41], 0x792080
	v_add_u32_e32 v253, 0xa000, v254
	v_mfma_f32_16x16x32_bf16 v[80:83], v[152:155], v[192:195], v[80:83]
	ds_read_b128 v[212:215], v251 offset:6144
	global_load_lds_dwordx4 v[232:233], off
	v_lshl_add_u64 v[232:233], v[174:175], 0, s[40:41]
	v_readfirstlane_b32 s40, v253
	v_mfma_f32_16x16x32_bf16 v[72:75], v[156:159], v[178:181], v[72:75]
	s_mov_b32 m0, s40
	s_mov_b64 s[40:41], 0x7b4080
	v_add_u32_e32 v253, 0xc000, v254
	v_mfma_f32_16x16x32_bf16 v[64:67], v[156:159], v[182:185], v[64:67]
	global_load_lds_dwordx4 v[232:233], off
	v_lshl_add_u64 v[232:233], v[174:175], 0, s[40:41]
	v_readfirstlane_b32 s40, v253
	v_mfma_f32_16x16x32_bf16 v[56:59], v[156:159], v[186:189], v[56:59]
	s_mov_b32 m0, s40
	s_mov_b64 s[40:41], 0x7d6080
	v_add_u32_e32 v254, 0xe000, v254
	v_mfma_f32_16x16x32_bf16 v[48:51], v[156:159], v[192:195], v[48:51]
	v_lshl_add_u64 v[174:175], v[174:175], 0, s[40:41]
	v_readfirstlane_b32 s40, v254
	global_load_lds_dwordx4 v[232:233], off
	v_mfma_f32_16x16x32_bf16 v[40:43], v[170:173], v[178:181], v[40:43]
	s_mov_b32 m0, s40
	global_load_lds_dwordx4 v[174:175], off
	v_mfma_f32_16x16x32_bf16 v[32:35], v[170:173], v[182:185], v[32:35]
	v_mfma_f32_16x16x32_bf16 v[24:27], v[170:173], v[186:189], v[24:27]
	v_mfma_f32_16x16x32_bf16 v[16:19], v[170:173], v[192:195], v[16:19]
	s_waitcnt lgkmcnt(4)
	v_mfma_f32_16x16x32_bf16 v[100:103], v[148:151], v[216:219], v[100:103]
	v_mfma_f32_16x16x32_bf16 v[92:95], v[148:151], v[220:223], v[92:95]
	v_mfma_f32_16x16x32_bf16 v[84:87], v[148:151], v[224:227], v[84:87]
	ds_read_b128 v[178:181], v250 offset:32768
	v_mfma_f32_16x16x32_bf16 v[76:79], v[148:151], v[228:231], v[76:79]
	ds_read_b128 v[182:185], v250 offset:34816
	v_mfma_f32_16x16x32_bf16 v[68:71], v[152:155], v[216:219], v[68:71]
	ds_read_b128 v[186:189], v250 offset:36864
	v_mfma_f32_16x16x32_bf16 v[60:63], v[152:155], v[220:223], v[60:63]
	ds_read_b128 v[192:195], v250 offset:38912
	v_mfma_f32_16x16x32_bf16 v[52:55], v[152:155], v[224:227], v[52:55]
	v_mfma_f32_16x16x32_bf16 v[44:47], v[152:155], v[228:231], v[44:47]
	v_mfma_f32_16x16x32_bf16 v[36:39], v[156:159], v[216:219], v[36:39]
	v_mfma_f32_16x16x32_bf16 v[28:31], v[156:159], v[220:223], v[28:31]
	v_mfma_f32_16x16x32_bf16 v[20:23], v[156:159], v[224:227], v[20:23]
	v_mfma_f32_16x16x32_bf16 v[12:15], v[156:159], v[228:231], v[12:15]
	v_mfma_f32_16x16x32_bf16 v[8:11], v[170:173], v[216:219], v[8:11]
	v_mfma_f32_16x16x32_bf16 v[4:7], v[170:173], v[220:223], v[4:7]
	v_mfma_f32_16x16x32_bf16 v[0:3], v[170:173], v[224:227], v[0:3]
	v_mfma_f32_16x16x32_bf16 v[108:111], v[170:173], v[228:231], v[108:111]
	s_waitcnt lgkmcnt(0)
	v_mfma_f32_16x16x32_bf16 v[124:127], v[198:201], v[178:181], v[124:127]
	ds_read_b128 v[216:219], v250 offset:40960
	v_mfma_f32_16x16x32_bf16 v[120:123], v[198:201], v[182:185], v[120:123]
	ds_read_b128 v[220:223], v250 offset:43008
	v_mfma_f32_16x16x32_bf16 v[116:119], v[198:201], v[186:189], v[116:119]
	ds_read_b128 v[224:227], v250 offset:45056
	v_mfma_f32_16x16x32_bf16 v[112:115], v[198:201], v[192:195], v[112:115]
	ds_read_b128 v[228:231], v250 offset:47104
	v_mfma_f32_16x16x32_bf16 v[104:107], v[204:207], v[178:181], v[104:107]
	v_mfma_f32_16x16x32_bf16 v[96:99], v[204:207], v[182:185], v[96:99]
	v_mfma_f32_16x16x32_bf16 v[88:91], v[204:207], v[186:189], v[88:91]
	v_mfma_f32_16x16x32_bf16 v[80:83], v[204:207], v[192:195], v[80:83]
	v_mfma_f32_16x16x32_bf16 v[72:75], v[208:211], v[178:181], v[72:75]
	v_mfma_f32_16x16x32_bf16 v[64:67], v[208:211], v[182:185], v[64:67]
	v_mfma_f32_16x16x32_bf16 v[56:59], v[208:211], v[186:189], v[56:59]
	v_mfma_f32_16x16x32_bf16 v[48:51], v[208:211], v[192:195], v[48:51]
	v_mfma_f32_16x16x32_bf16 v[40:43], v[212:215], v[178:181], v[40:43]
	v_mfma_f32_16x16x32_bf16 v[32:35], v[212:215], v[182:185], v[32:35]
	v_mfma_f32_16x16x32_bf16 v[24:27], v[212:215], v[186:189], v[24:27]
	v_mfma_f32_16x16x32_bf16 v[16:19], v[212:215], v[192:195], v[16:19]
	s_waitcnt lgkmcnt(0)
	v_mfma_f32_16x16x32_bf16 v[100:103], v[198:201], v[216:219], v[100:103]
	v_mfma_f32_16x16x32_bf16 v[92:95], v[198:201], v[220:223], v[92:95]
	v_mfma_f32_16x16x32_bf16 v[84:87], v[198:201], v[224:227], v[84:87]
	v_mfma_f32_16x16x32_bf16 v[76:79], v[198:201], v[228:231], v[76:79]
	v_mfma_f32_16x16x32_bf16 v[68:71], v[204:207], v[216:219], v[68:71]
	v_mfma_f32_16x16x32_bf16 v[60:63], v[204:207], v[220:223], v[60:63]
	v_mfma_f32_16x16x32_bf16 v[52:55], v[204:207], v[224:227], v[52:55]
	v_mfma_f32_16x16x32_bf16 v[44:47], v[204:207], v[228:231], v[44:47]
	v_mfma_f32_16x16x32_bf16 v[36:39], v[208:211], v[216:219], v[36:39]
	v_mfma_f32_16x16x32_bf16 v[28:31], v[208:211], v[220:223], v[28:31]
	v_mfma_f32_16x16x32_bf16 v[20:23], v[208:211], v[224:227], v[20:23]
	v_mfma_f32_16x16x32_bf16 v[12:15], v[208:211], v[228:231], v[12:15]
	s_add_u32 s2, s2, 0x80
	s_addc_u32 s3, s3, 0
	s_cmpk_eq_i32 s2, 0x780
	s_mov_b32 s4, s5
	v_mfma_f32_16x16x32_bf16 v[8:11], v[212:215], v[216:219], v[8:11]
	v_mfma_f32_16x16x32_bf16 v[4:7], v[212:215], v[220:223], v[4:7]
	v_mfma_f32_16x16x32_bf16 v[0:3], v[212:215], v[224:227], v[0:3]
	v_mfma_f32_16x16x32_bf16 v[108:111], v[212:215], v[228:231], v[108:111]
	s_cbranch_scc0 .LBB0_1074
	s_add_i32 s2, 0, 0x10000
	v_add_u32_e32 v136, s2, v145
	v_add_u32_e32 v174, s2, v144
	v_add_u32_e32 v137, v136, v143
	v_add_u32_e32 v143, v174, v143
	s_waitcnt vmcnt(0)
	s_barrier
	ds_read_b128 v[128:131], v137 offset:38912
	ds_read_b128 v[132:135], v137 offset:36864
	ds_read_b128 v[146:149], v137 offset:34816
	ds_read_b128 v[150:153], v137 offset:32768
	ds_read_b128 v[154:157], v143 offset:6144
	ds_read_b128 v[158:161], v143 offset:4096
	ds_read_b128 v[170:173], v143 offset:2048
	ds_read_b128 v[178:181], v143
	s_waitcnt lgkmcnt(0)
	v_mfma_f32_16x16x32_bf16 v[124:127], v[178:181], v[150:153], v[124:127]
	v_mfma_f32_16x16x32_bf16 v[120:123], v[178:181], v[146:149], v[120:123]
	v_mfma_f32_16x16x32_bf16 v[116:119], v[178:181], v[132:135], v[116:119]
	v_mfma_f32_16x16x32_bf16 v[112:115], v[178:181], v[128:131], v[112:115]
	v_mfma_f32_16x16x32_bf16 v[104:107], v[170:173], v[150:153], v[104:107]
	v_mfma_f32_16x16x32_bf16 v[72:75], v[158:161], v[150:153], v[72:75]
	v_mfma_f32_16x16x32_bf16 v[64:67], v[158:161], v[146:149], v[64:67]
	v_mfma_f32_16x16x32_bf16 v[56:59], v[158:161], v[132:135], v[56:59]
	v_mfma_f32_16x16x32_bf16 v[48:51], v[158:161], v[128:131], v[48:51]
	v_mfma_f32_16x16x32_bf16 v[182:185], v[170:173], v[146:149], v[96:99]
	v_mfma_f32_16x16x32_bf16 v[186:189], v[170:173], v[132:135], v[88:91]
	v_mfma_f32_16x16x32_bf16 v[192:195], v[170:173], v[128:131], v[80:83]
	v_mfma_f32_16x16x32_bf16 v[150:153], v[154:157], v[150:153], v[40:43]
	v_mfma_f32_16x16x32_bf16 v[144:147], v[154:157], v[146:149], v[32:35]
	v_mfma_f32_16x16x32_bf16 v[132:135], v[154:157], v[132:135], v[24:27]
	v_mfma_f32_16x16x32_bf16 v[128:131], v[154:157], v[128:131], v[16:19]
	s_nop 2
	ds_read_b128 v[16:19], v137 offset:40960
	ds_read_b128 v[24:27], v137 offset:43008
	ds_read_b128 v[32:35], v137 offset:45056
	ds_read_b128 v[40:43], v137 offset:47104
	s_waitcnt lgkmcnt(0)
	v_mfma_f32_16x16x32_bf16 v[100:103], v[178:181], v[16:19], v[100:103]
	v_mfma_f32_16x16x32_bf16 v[92:95], v[178:181], v[24:27], v[92:95]
	v_mfma_f32_16x16x32_bf16 v[198:201], v[178:181], v[32:35], v[84:87]
	v_mfma_f32_16x16x32_bf16 v[76:79], v[178:181], v[40:43], v[76:79]
	v_mfma_f32_16x16x32_bf16 v[68:71], v[170:173], v[16:19], v[68:71]
	v_mfma_f32_16x16x32_bf16 v[60:63], v[170:173], v[24:27], v[60:63]
	v_mfma_f32_16x16x32_bf16 v[178:181], v[170:173], v[32:35], v[52:55]
	v_mfma_f32_16x16x32_bf16 v[44:47], v[170:173], v[40:43], v[44:47]
	v_mfma_f32_16x16x32_bf16 v[170:173], v[158:161], v[16:19], v[36:39]
	v_mfma_f32_16x16x32_bf16 v[204:207], v[158:161], v[24:27], v[28:31]
	v_mfma_f32_16x16x32_bf16 v[208:211], v[158:161], v[32:35], v[20:23]
	v_mfma_f32_16x16x32_bf16 v[158:161], v[158:161], v[40:43], v[12:15]
	v_mfma_f32_16x16x32_bf16 v[212:215], v[154:157], v[16:19], v[8:11]
	v_mfma_f32_16x16x32_bf16 v[216:219], v[154:157], v[24:27], v[4:7]
	v_mfma_f32_16x16x32_bf16 v[220:223], v[154:157], v[32:35], v[0:3]
	v_mfma_f32_16x16x32_bf16 v[154:157], v[154:157], v[40:43], v[108:111]
	s_nop 1
	v_add_u32_e32 v0, v174, v142
	v_add_u32_e32 v136, v136, v142
	ds_read_b128 v[108:111], v0
	ds_read_b128 v[224:227], v0 offset:2048
	ds_read_b128 v[228:231], v0 offset:4096
	ds_read_b128 v[232:235], v0 offset:6144
	ds_read_b128 v[0:3], v136 offset:32768
	ds_read_b128 v[4:7], v136 offset:34816
	ds_read_b128 v[236:239], v136 offset:36864
	ds_read_b128 v[240:243], v136 offset:38912
	s_waitcnt lgkmcnt(0)
	v_mfma_f32_16x16x32_bf16 v[88:91], v[108:111], v[0:3], v[124:127]
	v_mfma_f32_16x16x32_bf16 v[96:99], v[108:111], v[4:7], v[120:123]
	v_mfma_f32_16x16x32_bf16 v[80:83], v[108:111], v[236:239], v[116:119]
	v_mfma_f32_16x16x32_bf16 v[84:87], v[108:111], v[240:243], v[112:115]
	v_mfma_f32_16x16x32_bf16 v[40:43], v[224:227], v[0:3], v[104:107]
	v_mfma_f32_16x16x32_bf16 v[52:55], v[224:227], v[4:7], v[182:185]
	v_mfma_f32_16x16x32_bf16 v[32:35], v[224:227], v[236:239], v[186:189]
	v_mfma_f32_16x16x32_bf16 v[36:39], v[224:227], v[240:243], v[192:195]
	v_mfma_f32_16x16x32_bf16 v[24:27], v[228:231], v[0:3], v[72:75]
	v_mfma_f32_16x16x32_bf16 v[28:31], v[228:231], v[4:7], v[64:67]
	v_mfma_f32_16x16x32_bf16 v[16:19], v[228:231], v[236:239], v[56:59]
	v_mfma_f32_16x16x32_bf16 v[20:23], v[228:231], v[240:243], v[48:51]
	v_mfma_f32_16x16x32_bf16 v[8:11], v[232:235], v[0:3], v[150:153]
	v_mfma_f32_16x16x32_bf16 v[12:15], v[232:235], v[4:7], v[144:147]
	v_mfma_f32_16x16x32_bf16 v[0:3], v[232:235], v[236:239], v[132:135]
	v_mfma_f32_16x16x32_bf16 v[4:7], v[232:235], v[240:243], v[128:131]
	ds_read_b128 v[48:51], v136 offset:40960
	ds_read_b128 v[64:67], v136 offset:43008
	s_nop 0
	ds_read_b128 v[128:131], v136 offset:45056
	ds_read_b128 v[132:135], v136 offset:47104
	s_waitcnt lgkmcnt(0)
	v_mfma_f32_16x16x32_bf16 v[104:107], v[224:227], v[48:51], v[68:71]
	v_cmp_ne_u32_e32 vcc, 0, v138
	v_cmp_eq_u32_e64 s[2:3], 0, v138
	s_waitcnt vmcnt(0)
	v_lshl_or_b32 v68, v140, 2, v141
	v_lshl_add_u32 v69, v139, 2, 0
	v_mfma_f32_16x16x32_bf16 v[120:123], v[108:111], v[48:51], v[100:103]
	s_barrier
	v_mfma_f32_16x16x32_bf16 v[124:127], v[108:111], v[64:67], v[92:95]
	v_mfma_f32_16x16x32_bf16 v[112:115], v[108:111], v[128:131], v[198:201]
	v_mfma_f32_16x16x32_bf16 v[116:119], v[108:111], v[132:135], v[76:79]
	v_mfma_f32_16x16x32_bf16 v[108:111], v[224:227], v[64:67], v[60:63]
	v_mfma_f32_16x16x32_bf16 v[92:95], v[224:227], v[128:131], v[178:181]
	v_mfma_f32_16x16x32_bf16 v[100:103], v[224:227], v[132:135], v[44:47]
	s_nop 1
	v_lshl_add_u32 v178, v68, 9, v69
	v_add_u32_e32 v179, 0x400, v178
	v_add_u32_e32 v176, 0x2000, v178
	v_mfma_f32_16x16x32_bf16 v[56:59], v[228:231], v[48:51], v[170:173]
	v_add_u32_e32 v175, 0x2400, v178
	v_add_u32_e32 v174, 0x4000, v178
	v_mfma_f32_16x16x32_bf16 v[60:63], v[228:231], v[64:67], v[204:207]
	v_add_u32_e32 v173, 0x4400, v178
	v_add_u32_e32 v172, 0x6000, v178
	v_add_u32_e32 v171, 0x6400, v178
	v_mfma_f32_16x16x32_bf16 v[44:47], v[228:231], v[128:131], v[208:211]
	v_mfma_f32_16x16x32_bf16 v[72:75], v[228:231], v[132:135], v[158:161]
	v_mfma_f32_16x16x32_bf16 v[48:51], v[232:235], v[48:51], v[212:215]
	v_mfma_f32_16x16x32_bf16 v[64:67], v[232:235], v[64:67], v[216:219]
	v_mfma_f32_16x16x32_bf16 v[68:71], v[232:235], v[128:131], v[220:223]
	v_mfma_f32_16x16x32_bf16 v[76:79], v[232:235], v[132:135], v[154:157]
	s_and_saveexec_b64 s[4:5], s[2:3]
	s_cbranch_execz .LBB0_1077
	ds_write2_b32 v178, v88, v96 offset1:16
	ds_write2_b32 v178, v89, v97 offset0:128 offset1:144
	ds_write2_b32 v179, v90, v98 offset1:16
	ds_write2_b32 v179, v91, v99 offset0:128 offset1:144
	ds_write2_b32 v178, v80, v84 offset0:32 offset1:48
	ds_write2_b32 v178, v81, v85 offset0:160 offset1:176
	ds_write2_b32 v179, v82, v86 offset0:32 offset1:48
	ds_write2_b32 v179, v83, v87 offset0:160 offset1:176
	ds_write2_b32 v178, v120, v124 offset0:64 offset1:80
	ds_write2_b32 v178, v121, v125 offset0:192 offset1:208
	ds_write2_b32 v179, v122, v126 offset0:64 offset1:80
	ds_write2_b32 v179, v123, v127 offset0:192 offset1:208
	ds_write2_b32 v178, v112, v116 offset0:96 offset1:112
	ds_write2_b32 v178, v113, v117 offset0:224 offset1:240
	ds_write2_b32 v179, v114, v118 offset0:96 offset1:112
	ds_write2_b32 v179, v115, v119 offset0:224 offset1:240
	ds_write2_b32 v176, v40, v52 offset1:16
	ds_write2_b32 v176, v41, v53 offset0:128 offset1:144
	ds_write2_b32 v175, v42, v54 offset1:16
	ds_write2_b32 v175, v43, v55 offset0:128 offset1:144
	ds_write2_b32 v176, v32, v36 offset0:32 offset1:48
	ds_write2_b32 v176, v33, v37 offset0:160 offset1:176
	ds_write2_b32 v175, v34, v38 offset0:32 offset1:48
	ds_write2_b32 v175, v35, v39 offset0:160 offset1:176
	ds_write2_b32 v176, v104, v108 offset0:64 offset1:80
	ds_write2_b32 v176, v105, v109 offset0:192 offset1:208
	ds_write2_b32 v175, v106, v110 offset0:64 offset1:80
	ds_write2_b32 v175, v107, v111 offset0:192 offset1:208
	ds_write2_b32 v176, v92, v100 offset0:96 offset1:112
	ds_write2_b32 v176, v93, v101 offset0:224 offset1:240
	ds_write2_b32 v175, v94, v102 offset0:96 offset1:112
	ds_write2_b32 v175, v95, v103 offset0:224 offset1:240
	ds_write2_b32 v174, v24, v28 offset1:16
	ds_write2_b32 v174, v25, v29 offset0:128 offset1:144
	ds_write2_b32 v173, v26, v30 offset1:16
	ds_write2_b32 v173, v27, v31 offset0:128 offset1:144
	ds_write2_b32 v174, v16, v20 offset0:32 offset1:48
	ds_write2_b32 v174, v17, v21 offset0:160 offset1:176
	ds_write2_b32 v173, v18, v22 offset0:32 offset1:48
	ds_write2_b32 v173, v19, v23 offset0:160 offset1:176
	ds_write2_b32 v174, v56, v60 offset0:64 offset1:80
	ds_write2_b32 v174, v57, v61 offset0:192 offset1:208
	ds_write2_b32 v173, v58, v62 offset0:64 offset1:80
	ds_write2_b32 v173, v59, v63 offset0:192 offset1:208
	ds_write2_b32 v174, v44, v72 offset0:96 offset1:112
	ds_write2_b32 v174, v45, v73 offset0:224 offset1:240
	ds_write2_b32 v173, v46, v74 offset0:96 offset1:112
	ds_write2_b32 v173, v47, v75 offset0:224 offset1:240
	ds_write2_b32 v172, v8, v12 offset1:16
	ds_write2_b32 v172, v9, v13 offset0:128 offset1:144
	ds_write2_b32 v171, v10, v14 offset1:16
	ds_write2_b32 v171, v11, v15 offset0:128 offset1:144
	ds_write2_b32 v172, v0, v4 offset0:32 offset1:48
	ds_write2_b32 v172, v1, v5 offset0:160 offset1:176
	ds_write2_b32 v171, v2, v6 offset0:32 offset1:48
	ds_write2_b32 v171, v3, v7 offset0:160 offset1:176
	ds_write2_b32 v172, v48, v64 offset0:64 offset1:80
	ds_write2_b32 v172, v49, v65 offset0:192 offset1:208
	ds_write2_b32 v171, v50, v66 offset0:64 offset1:80
	ds_write2_b32 v171, v51, v67 offset0:192 offset1:208
	ds_write2_b32 v172, v68, v76 offset0:96 offset1:112
	ds_write2_b32 v172, v69, v77 offset0:224 offset1:240
	ds_write2_b32 v171, v70, v78 offset0:96 offset1:112
	ds_write2_b32 v171, v71, v79 offset0:224 offset1:240

.LBB0_1143:
	s_add_i32 s11, s10, 0x10000
	s_and_b32 s19, s11, 0x10000
	s_waitcnt vmcnt(0)
	s_barrier
	s_and_b32 s10, s10, 0x10000
	s_add_i32 s10, s10, 0
	v_add_u32_e32 v151, s10, v149
	v_add_u32_e32 v164, v151, v147
	ds_read_b128 v[152:155], v164
	ds_read_b128 v[156:159], v164 offset:2048
	ds_read_b128 v[160:163], v164 offset:4096
	ds_read_b128 v[164:167], v164 offset:6144
	v_add_u32_e32 v251, v151, v146
	v_add_u32_e32 v176, s10, v148
	v_add_u32_e32 v186, v176, v147
	ds_read_b128 v[168:171], v186 offset:32768
	ds_read_b128 v[172:175], v186 offset:34816
	ds_read_b128 v[178:181], v186 offset:36864
	ds_read_b128 v[182:185], v186 offset:38912
	v_add_u32_e32 v250, v176, v146
	v_add_u32_e32 v254, s19, v150
	v_add_u32_e32 v228, 0x2000, v254
	v_readfirstlane_b32 s19, v254
	v_lshl_add_u64 v[188:189], v[128:129], 0, s[2:3]
	s_mov_b32 m0, s19
	v_readfirstlane_b32 s19, v228
	v_add_u32_e32 v228, 0x4000, v254
	global_load_lds_dwordx4 v[188:189], off
	v_lshl_add_u64 v[188:189], v[130:131], 0, s[2:3]
	s_mov_b32 m0, s19
	s_waitcnt lgkmcnt(0)
	v_mfma_f32_16x16x32_bf16 v[124:127], v[152:155], v[168:171], v[124:127]
	ds_read_b128 v[212:215], v186 offset:40960
	v_mfma_f32_16x16x32_bf16 v[120:123], v[152:155], v[172:175], v[120:123]
	ds_read_b128 v[216:219], v186 offset:43008
	v_readfirstlane_b32 s19, v228
	v_add_u32_e32 v228, 0x6000, v254
	global_load_lds_dwordx4 v[188:189], off
	v_mfma_f32_16x16x32_bf16 v[116:119], v[152:155], v[178:181], v[116:119]
	ds_read_b128 v[220:223], v186 offset:45056
	v_lshl_add_u64 v[188:189], v[132:133], 0, s[2:3]
	s_mov_b32 m0, s19
	v_readfirstlane_b32 s19, v228
	v_mfma_f32_16x16x32_bf16 v[112:115], v[152:155], v[182:185], v[112:115]
	ds_read_b128 v[224:227], v186 offset:47104
	global_load_lds_dwordx4 v[188:189], off
	v_lshl_add_u64 v[188:189], v[134:135], 0, s[2:3]
	s_mov_b32 m0, s19
	v_mfma_f32_16x16x32_bf16 v[104:107], v[156:159], v[168:171], v[104:107]
	ds_read_b128 v[192:195], v251
	v_add_u32_e32 v253, 0x8000, v254
	global_load_lds_dwordx4 v[188:189], off
	v_lshl_add_u64 v[188:189], v[136:137], 0, s[2:3]
	v_mfma_f32_16x16x32_bf16 v[96:99], v[156:159], v[172:175], v[96:99]
	ds_read_b128 v[198:201], v251 offset:2048
	s_mov_b64 s[20:21], 0x1320080
	v_readfirstlane_b32 s19, v253
	v_add_u32_e32 v253, 0xa000, v254
	v_mfma_f32_16x16x32_bf16 v[88:91], v[156:159], v[178:181], v[88:91]
	ds_read_b128 v[204:207], v251 offset:4096
	v_lshl_add_u64 v[228:229], v[188:189], 0, s[20:21]
	s_mov_b32 m0, s19
	s_mov_b64 s[20:21], 0x1378080
	v_mfma_f32_16x16x32_bf16 v[80:83], v[156:159], v[182:185], v[80:83]
	ds_read_b128 v[208:211], v251 offset:6144
	v_readfirstlane_b32 s19, v253
	v_add_u32_e32 v253, 0xc000, v254
	global_load_lds_dwordx4 v[228:229], off
	v_mfma_f32_16x16x32_bf16 v[72:75], v[160:163], v[168:171], v[72:75]
	v_lshl_add_u64 v[228:229], v[188:189], 0, s[20:21]
	s_mov_b32 m0, s19
	s_mov_b64 s[20:21], 0x13d0080
	v_mfma_f32_16x16x32_bf16 v[64:67], v[160:163], v[172:175], v[64:67]
	v_readfirstlane_b32 s19, v253
	v_add_u32_e32 v254, 0xe000, v254
	global_load_lds_dwordx4 v[228:229], off
	v_mfma_f32_16x16x32_bf16 v[56:59], v[160:163], v[178:181], v[56:59]
	v_lshl_add_u64 v[228:229], v[188:189], 0, s[20:21]
	s_mov_b32 m0, s19
	s_mov_b64 s[20:21], 0x1428080
	v_mfma_f32_16x16x32_bf16 v[48:51], v[160:163], v[182:185], v[48:51]
	v_readfirstlane_b32 s19, v254
	global_load_lds_dwordx4 v[228:229], off
	v_lshl_add_u64 v[188:189], v[188:189], 0, s[20:21]
	v_mfma_f32_16x16x32_bf16 v[40:43], v[164:167], v[168:171], v[40:43]
	s_mov_b32 m0, s19
	global_load_lds_dwordx4 v[188:189], off
	v_mfma_f32_16x16x32_bf16 v[32:35], v[164:167], v[172:175], v[32:35]
	v_mfma_f32_16x16x32_bf16 v[24:27], v[164:167], v[178:181], v[24:27]
	v_mfma_f32_16x16x32_bf16 v[16:19], v[164:167], v[182:185], v[16:19]
	s_waitcnt lgkmcnt(4)
	v_mfma_f32_16x16x32_bf16 v[100:103], v[152:155], v[212:215], v[100:103]
	v_mfma_f32_16x16x32_bf16 v[92:95], v[152:155], v[216:219], v[92:95]
	v_mfma_f32_16x16x32_bf16 v[84:87], v[152:155], v[220:223], v[84:87]
	ds_read_b128 v[168:171], v250 offset:32768
	v_mfma_f32_16x16x32_bf16 v[76:79], v[152:155], v[224:227], v[76:79]
	ds_read_b128 v[172:175], v250 offset:34816
	v_mfma_f32_16x16x32_bf16 v[68:71], v[156:159], v[212:215], v[68:71]
	ds_read_b128 v[178:181], v250 offset:36864
	v_mfma_f32_16x16x32_bf16 v[60:63], v[156:159], v[216:219], v[60:63]
	ds_read_b128 v[182:185], v250 offset:38912
	v_mfma_f32_16x16x32_bf16 v[52:55], v[156:159], v[220:223], v[52:55]
	v_mfma_f32_16x16x32_bf16 v[44:47], v[156:159], v[224:227], v[44:47]
	v_mfma_f32_16x16x32_bf16 v[36:39], v[160:163], v[212:215], v[36:39]
	v_mfma_f32_16x16x32_bf16 v[28:31], v[160:163], v[216:219], v[28:31]
	v_mfma_f32_16x16x32_bf16 v[20:23], v[160:163], v[220:223], v[20:23]
	v_mfma_f32_16x16x32_bf16 v[12:15], v[160:163], v[224:227], v[12:15]
	v_mfma_f32_16x16x32_bf16 v[8:11], v[164:167], v[212:215], v[8:11]
	v_mfma_f32_16x16x32_bf16 v[4:7], v[164:167], v[216:219], v[4:7]
	v_mfma_f32_16x16x32_bf16 v[0:3], v[164:167], v[220:223], v[0:3]
	v_mfma_f32_16x16x32_bf16 v[108:111], v[164:167], v[224:227], v[108:111]
	s_waitcnt lgkmcnt(0)
	v_mfma_f32_16x16x32_bf16 v[124:127], v[192:195], v[168:171], v[124:127]
	ds_read_b128 v[212:215], v250 offset:40960
	v_mfma_f32_16x16x32_bf16 v[120:123], v[192:195], v[172:175], v[120:123]
	ds_read_b128 v[216:219], v250 offset:43008
	v_mfma_f32_16x16x32_bf16 v[116:119], v[192:195], v[178:181], v[116:119]
	ds_read_b128 v[220:223], v250 offset:45056
	v_mfma_f32_16x16x32_bf16 v[112:115], v[192:195], v[182:185], v[112:115]
	ds_read_b128 v[224:227], v250 offset:47104
	v_mfma_f32_16x16x32_bf16 v[104:107], v[198:201], v[168:171], v[104:107]
	v_mfma_f32_16x16x32_bf16 v[96:99], v[198:201], v[172:175], v[96:99]
	v_mfma_f32_16x16x32_bf16 v[88:91], v[198:201], v[178:181], v[88:91]
	v_mfma_f32_16x16x32_bf16 v[80:83], v[198:201], v[182:185], v[80:83]
	v_mfma_f32_16x16x32_bf16 v[72:75], v[204:207], v[168:171], v[72:75]
	v_mfma_f32_16x16x32_bf16 v[64:67], v[204:207], v[172:175], v[64:67]
	v_mfma_f32_16x16x32_bf16 v[56:59], v[204:207], v[178:181], v[56:59]
	v_mfma_f32_16x16x32_bf16 v[48:51], v[204:207], v[182:185], v[48:51]
	v_mfma_f32_16x16x32_bf16 v[40:43], v[208:211], v[168:171], v[40:43]
	v_mfma_f32_16x16x32_bf16 v[32:35], v[208:211], v[172:175], v[32:35]
	v_mfma_f32_16x16x32_bf16 v[24:27], v[208:211], v[178:181], v[24:27]
	v_mfma_f32_16x16x32_bf16 v[16:19], v[208:211], v[182:185], v[16:19]
	s_waitcnt lgkmcnt(0)
	v_mfma_f32_16x16x32_bf16 v[100:103], v[192:195], v[212:215], v[100:103]
	v_mfma_f32_16x16x32_bf16 v[92:95], v[192:195], v[216:219], v[92:95]
	v_mfma_f32_16x16x32_bf16 v[84:87], v[192:195], v[220:223], v[84:87]
	v_mfma_f32_16x16x32_bf16 v[76:79], v[192:195], v[224:227], v[76:79]
	v_mfma_f32_16x16x32_bf16 v[68:71], v[198:201], v[212:215], v[68:71]
	v_mfma_f32_16x16x32_bf16 v[60:63], v[198:201], v[216:219], v[60:63]
	v_mfma_f32_16x16x32_bf16 v[52:55], v[198:201], v[220:223], v[52:55]
	v_mfma_f32_16x16x32_bf16 v[44:47], v[198:201], v[224:227], v[44:47]
	v_mfma_f32_16x16x32_bf16 v[36:39], v[204:207], v[212:215], v[36:39]
	v_mfma_f32_16x16x32_bf16 v[28:31], v[204:207], v[216:219], v[28:31]
	v_mfma_f32_16x16x32_bf16 v[20:23], v[204:207], v[220:223], v[20:23]
	v_mfma_f32_16x16x32_bf16 v[12:15], v[204:207], v[224:227], v[12:15]
	s_add_u32 s2, s2, 0x80
	s_addc_u32 s3, s3, 0
	s_cmpk_eq_i32 s2, 0x1580
	s_mov_b32 s10, s11
	v_mfma_f32_16x16x32_bf16 v[8:11], v[208:211], v[212:215], v[8:11]
	v_mfma_f32_16x16x32_bf16 v[4:7], v[208:211], v[216:219], v[4:7]
	v_mfma_f32_16x16x32_bf16 v[0:3], v[208:211], v[220:223], v[0:3]
	v_mfma_f32_16x16x32_bf16 v[108:111], v[208:211], v[224:227], v[108:111]
	s_cbranch_scc0 .LBB0_1143
	s_add_i32 s2, 0, 0x10000
	v_add_u32_e32 v136, s2, v149
	v_add_u32_e32 v137, v136, v147
	s_waitcnt vmcnt(0)
	s_barrier
	ds_read_b128 v[128:131], v137
	ds_read_b128 v[132:135], v137 offset:2048
	ds_read_b128 v[150:153], v137 offset:4096
	ds_read_b128 v[154:157], v137 offset:6144
	v_add_u32_e32 v137, s2, v148
	v_add_u32_e32 v147, v137, v147
	ds_read_b128 v[158:161], v147 offset:32768
	ds_read_b128 v[162:165], v147 offset:34816
	ds_read_b128 v[166:169], v147 offset:36864
	ds_read_b128 v[170:173], v147 offset:38912
	s_waitcnt lgkmcnt(0)
	v_mfma_f32_16x16x32_bf16 v[124:127], v[128:131], v[158:161], v[124:127]
	v_mfma_f32_16x16x32_bf16 v[120:123], v[128:131], v[162:165], v[120:123]
	v_mfma_f32_16x16x32_bf16 v[116:119], v[128:131], v[166:169], v[116:119]
	v_mfma_f32_16x16x32_bf16 v[112:115], v[128:131], v[170:173], v[112:115]
	v_mfma_f32_16x16x32_bf16 v[104:107], v[132:135], v[158:161], v[104:107]
	v_mfma_f32_16x16x32_bf16 v[72:75], v[150:153], v[158:161], v[72:75]
	v_mfma_f32_16x16x32_bf16 v[64:67], v[150:153], v[162:165], v[64:67]
	v_mfma_f32_16x16x32_bf16 v[56:59], v[150:153], v[166:169], v[56:59]
	v_mfma_f32_16x16x32_bf16 v[48:51], v[150:153], v[170:173], v[48:51]
	v_mfma_f32_16x16x32_bf16 v[178:181], v[132:135], v[162:165], v[96:99]
	v_mfma_f32_16x16x32_bf16 v[182:185], v[132:135], v[166:169], v[88:91]
	v_mfma_f32_16x16x32_bf16 v[186:189], v[132:135], v[170:173], v[80:83]
	v_mfma_f32_16x16x32_bf16 v[158:161], v[154:157], v[158:161], v[40:43]
	v_mfma_f32_16x16x32_bf16 v[162:165], v[154:157], v[162:165], v[32:35]
	v_mfma_f32_16x16x32_bf16 v[166:169], v[154:157], v[166:169], v[24:27]
	v_mfma_f32_16x16x32_bf16 v[170:173], v[154:157], v[170:173], v[16:19]
	s_nop 2
	ds_read_b128 v[16:19], v147 offset:40960
	ds_read_b128 v[24:27], v147 offset:43008
	ds_read_b128 v[32:35], v147 offset:45056
	ds_read_b128 v[40:43], v147 offset:47104
	s_waitcnt lgkmcnt(0)
	v_mfma_f32_16x16x32_bf16 v[100:103], v[128:131], v[16:19], v[100:103]
	v_mfma_f32_16x16x32_bf16 v[92:95], v[128:131], v[24:27], v[92:95]
	v_mfma_f32_16x16x32_bf16 v[192:195], v[128:131], v[32:35], v[84:87]
	v_mfma_f32_16x16x32_bf16 v[76:79], v[128:131], v[40:43], v[76:79]
	v_mfma_f32_16x16x32_bf16 v[68:71], v[132:135], v[16:19], v[68:71]
	v_mfma_f32_16x16x32_bf16 v[60:63], v[132:135], v[24:27], v[60:63]
	v_mfma_f32_16x16x32_bf16 v[128:131], v[132:135], v[32:35], v[52:55]
	v_mfma_f32_16x16x32_bf16 v[44:47], v[132:135], v[40:43], v[44:47]
	v_mfma_f32_16x16x32_bf16 v[132:135], v[150:153], v[16:19], v[36:39]
	v_mfma_f32_16x16x32_bf16 v[198:201], v[150:153], v[24:27], v[28:31]
	v_mfma_f32_16x16x32_bf16 v[204:207], v[150:153], v[32:35], v[20:23]
	v_mfma_f32_16x16x32_bf16 v[148:151], v[150:153], v[40:43], v[12:15]
	v_mfma_f32_16x16x32_bf16 v[208:211], v[154:157], v[16:19], v[8:11]
	v_mfma_f32_16x16x32_bf16 v[212:215], v[154:157], v[24:27], v[4:7]
	v_mfma_f32_16x16x32_bf16 v[216:219], v[154:157], v[32:35], v[0:3]
	v_mfma_f32_16x16x32_bf16 v[154:157], v[154:157], v[40:43], v[108:111]
	s_nop 1
	v_add_u32_e32 v0, v136, v146
	v_add_u32_e32 v136, v137, v146
	ds_read_b128 v[108:111], v0
	ds_read_b128 v[220:223], v0 offset:2048
	ds_read_b128 v[224:227], v0 offset:4096
	ds_read_b128 v[228:231], v0 offset:6144
	ds_read_b128 v[0:3], v136 offset:32768
	ds_read_b128 v[4:7], v136 offset:34816
	ds_read_b128 v[232:235], v136 offset:36864
	ds_read_b128 v[236:239], v136 offset:38912
	s_waitcnt lgkmcnt(0)
	v_mfma_f32_16x16x32_bf16 v[88:91], v[108:111], v[0:3], v[124:127]
	v_mfma_f32_16x16x32_bf16 v[96:99], v[108:111], v[4:7], v[120:123]
	v_mfma_f32_16x16x32_bf16 v[80:83], v[108:111], v[232:235], v[116:119]
	v_mfma_f32_16x16x32_bf16 v[84:87], v[108:111], v[236:239], v[112:115]
	v_mfma_f32_16x16x32_bf16 v[40:43], v[220:223], v[0:3], v[104:107]
	v_mfma_f32_16x16x32_bf16 v[52:55], v[220:223], v[4:7], v[178:181]
	v_mfma_f32_16x16x32_bf16 v[32:35], v[220:223], v[232:235], v[182:185]
	v_mfma_f32_16x16x32_bf16 v[36:39], v[220:223], v[236:239], v[186:189]
	v_mfma_f32_16x16x32_bf16 v[24:27], v[224:227], v[0:3], v[72:75]
	v_mfma_f32_16x16x32_bf16 v[28:31], v[224:227], v[4:7], v[64:67]
	v_mfma_f32_16x16x32_bf16 v[16:19], v[224:227], v[232:235], v[56:59]
	v_mfma_f32_16x16x32_bf16 v[20:23], v[224:227], v[236:239], v[48:51]
	v_mfma_f32_16x16x32_bf16 v[8:11], v[228:231], v[0:3], v[158:161]
	v_mfma_f32_16x16x32_bf16 v[12:15], v[228:231], v[4:7], v[162:165]
	v_mfma_f32_16x16x32_bf16 v[0:3], v[228:231], v[232:235], v[166:169]
	v_mfma_f32_16x16x32_bf16 v[4:7], v[228:231], v[236:239], v[170:173]
	ds_read_b128 v[48:51], v136 offset:40960
	ds_read_b128 v[64:67], v136 offset:43008
	ds_read_b128 v[158:161], v136 offset:45056
	ds_read_b128 v[162:165], v136 offset:47104
	s_waitcnt lgkmcnt(0)
	v_mfma_f32_16x16x32_bf16 v[104:107], v[220:223], v[48:51], v[68:71]
	v_cmp_ne_u32_e32 vcc, 0, v138
	v_cmp_eq_u32_e64 s[2:3], 0, v138
	s_waitcnt vmcnt(0)
	v_lshl_or_b32 v68, v140, 2, v141
	v_lshl_add_u32 v69, v139, 2, 0
	v_mfma_f32_16x16x32_bf16 v[120:123], v[108:111], v[48:51], v[100:103]
	v_lshl_add_u32 v152, v68, 9, v69
	v_add_u32_e32 v153, 0x400, v152
	v_add_u32_e32 v147, 0x6000, v152
	v_mfma_f32_16x16x32_bf16 v[124:127], v[108:111], v[64:67], v[92:95]
	v_add_u32_e32 v146, 0x6400, v152
	s_barrier
	v_mfma_f32_16x16x32_bf16 v[112:115], v[108:111], v[158:161], v[192:195]
	v_mfma_f32_16x16x32_bf16 v[116:119], v[108:111], v[162:165], v[76:79]
	v_mfma_f32_16x16x32_bf16 v[108:111], v[220:223], v[64:67], v[60:63]
	v_mfma_f32_16x16x32_bf16 v[92:95], v[220:223], v[158:161], v[128:131]
	v_mfma_f32_16x16x32_bf16 v[100:103], v[220:223], v[162:165], v[44:47]
	v_mfma_f32_16x16x32_bf16 v[56:59], v[224:227], v[48:51], v[132:135]
	v_mfma_f32_16x16x32_bf16 v[60:63], v[224:227], v[64:67], v[198:201]
	v_mfma_f32_16x16x32_bf16 v[44:47], v[224:227], v[158:161], v[204:207]
	v_mfma_f32_16x16x32_bf16 v[72:75], v[224:227], v[162:165], v[148:151]
	v_mfma_f32_16x16x32_bf16 v[48:51], v[228:231], v[48:51], v[208:211]
	s_nop 1
	v_add_u32_e32 v151, 0x2000, v152
	v_add_u32_e32 v150, 0x2400, v152
	v_add_u32_e32 v149, 0x4000, v152
	v_mfma_f32_16x16x32_bf16 v[64:67], v[228:231], v[64:67], v[212:215]
	v_add_u32_e32 v148, 0x4400, v152
	v_mfma_f32_16x16x32_bf16 v[68:71], v[228:231], v[158:161], v[216:219]
	v_mfma_f32_16x16x32_bf16 v[76:79], v[228:231], v[162:165], v[154:157]
	s_and_saveexec_b64 s[10:11], s[2:3]
	s_cbranch_execz .LBB0_1146
	ds_write2_b32 v152, v88, v96 offset1:16
	ds_write2_b32 v152, v89, v97 offset0:128 offset1:144
	ds_write2_b32 v153, v90, v98 offset1:16
	ds_write2_b32 v153, v91, v99 offset0:128 offset1:144
	ds_write2_b32 v152, v80, v84 offset0:32 offset1:48
	ds_write2_b32 v152, v81, v85 offset0:160 offset1:176
	ds_write2_b32 v153, v82, v86 offset0:32 offset1:48
	ds_write2_b32 v153, v83, v87 offset0:160 offset1:176
	ds_write2_b32 v152, v120, v124 offset0:64 offset1:80
	ds_write2_b32 v152, v121, v125 offset0:192 offset1:208
	ds_write2_b32 v153, v122, v126 offset0:64 offset1:80
	ds_write2_b32 v153, v123, v127 offset0:192 offset1:208
	ds_write2_b32 v152, v112, v116 offset0:96 offset1:112
	ds_write2_b32 v152, v113, v117 offset0:224 offset1:240
	ds_write2_b32 v153, v114, v118 offset0:96 offset1:112
	ds_write2_b32 v153, v115, v119 offset0:224 offset1:240
	ds_write2_b32 v151, v40, v52 offset1:16
	ds_write2_b32 v151, v41, v53 offset0:128 offset1:144
	ds_write2_b32 v150, v42, v54 offset1:16
	ds_write2_b32 v150, v43, v55 offset0:128 offset1:144
	ds_write2_b32 v151, v32, v36 offset0:32 offset1:48
	ds_write2_b32 v151, v33, v37 offset0:160 offset1:176
	ds_write2_b32 v150, v34, v38 offset0:32 offset1:48
	ds_write2_b32 v150, v35, v39 offset0:160 offset1:176
	ds_write2_b32 v151, v104, v108 offset0:64 offset1:80
	ds_write2_b32 v151, v105, v109 offset0:192 offset1:208
	ds_write2_b32 v150, v106, v110 offset0:64 offset1:80
	ds_write2_b32 v150, v107, v111 offset0:192 offset1:208
	ds_write2_b32 v151, v92, v100 offset0:96 offset1:112
	ds_write2_b32 v151, v93, v101 offset0:224 offset1:240
	ds_write2_b32 v150, v94, v102 offset0:96 offset1:112
	ds_write2_b32 v150, v95, v103 offset0:224 offset1:240
	ds_write2_b32 v149, v24, v28 offset1:16
	ds_write2_b32 v149, v25, v29 offset0:128 offset1:144
	ds_write2_b32 v148, v26, v30 offset1:16
	ds_write2_b32 v148, v27, v31 offset0:128 offset1:144
	ds_write2_b32 v149, v16, v20 offset0:32 offset1:48
	ds_write2_b32 v149, v17, v21 offset0:160 offset1:176
	ds_write2_b32 v148, v18, v22 offset0:32 offset1:48
	ds_write2_b32 v148, v19, v23 offset0:160 offset1:176
	ds_write2_b32 v149, v56, v60 offset0:64 offset1:80
	ds_write2_b32 v149, v57, v61 offset0:192 offset1:208
	ds_write2_b32 v148, v58, v62 offset0:64 offset1:80
	ds_write2_b32 v148, v59, v63 offset0:192 offset1:208
	ds_write2_b32 v149, v44, v72 offset0:96 offset1:112
	ds_write2_b32 v149, v45, v73 offset0:224 offset1:240
	ds_write2_b32 v148, v46, v74 offset0:96 offset1:112
	ds_write2_b32 v148, v47, v75 offset0:224 offset1:240
	ds_write2_b32 v147, v8, v12 offset1:16
	ds_write2_b32 v147, v9, v13 offset0:128 offset1:144
	ds_write2_b32 v146, v10, v14 offset1:16
	ds_write2_b32 v146, v11, v15 offset0:128 offset1:144
	ds_write2_b32 v147, v0, v4 offset0:32 offset1:48
	ds_write2_b32 v147, v1, v5 offset0:160 offset1:176
	ds_write2_b32 v146, v2, v6 offset0:32 offset1:48
	ds_write2_b32 v146, v3, v7 offset0:160 offset1:176
	ds_write2_b32 v147, v48, v64 offset0:64 offset1:80
	ds_write2_b32 v147, v49, v65 offset0:192 offset1:208
	ds_write2_b32 v146, v50, v66 offset0:64 offset1:80
	ds_write2_b32 v146, v51, v67 offset0:192 offset1:208
	ds_write2_b32 v147, v68, v76 offset0:96 offset1:112
	ds_write2_b32 v147, v69, v77 offset0:224 offset1:240
	ds_write2_b32 v146, v70, v78 offset0:96 offset1:112
	ds_write2_b32 v146, v71, v79 offset0:224 offset1:240
